# v41 + P4 pooling stores write-through (sc1), no L2 write-back at the P4->P5 seam
# speedup vs baseline: 1.0043x; 1.0043x over previous
; __device__ __forceinline__ unsigned cvt_pk_bf16(float lo, float hi) { unsigned r; asm volatile("v_cvt_pk_bf16_f32 %0, %1, %2" : "=v"(r) : "v"(lo), "v"(hi)); return r; }
; __device__ __forceinline__ float bf_lo(unsigned w) { return __uint_as_float(w << 16); }
; __device__ __forceinline__ float bf_hi(unsigned w) { return __uint_as_float(w & 0xffff0000u); }
; template <int W> __device__ __forceinline__ void pool_item(const bf16* zp, bf16* pl, int t0) {
;     unsigned zr[W - 1 + 32];
; #pragma unroll
;     for (int j = 0; j < W - 1 + 32; ++j) { const int tt = j - (W - 1); zr[j] = (t0 + tt >= 0) ? *(const unsigned*)(zp + (long)tt * NIN) : 0u; }
;     float s0 = 0.f, s1 = 0.f;
; #pragma unroll
;     for (int j = 0; j < W - 1; ++j) { s0 += pg8::bf_lo(zr[j]); s1 += pg8::bf_hi(zr[j]); }
; #pragma unroll
;     for (int tt = 0; tt < 32; ++tt) { const float z0 = pg8::bf_lo(zr[W - 1 + tt]), z1 = pg8::bf_hi(zr[W - 1 + tt]); s0 += z0; s1 += z1; const int t = t0 + tt;
;         const float iv = (t + 1 >= W ? 1.0f / (float)W : 1.0f / (float)(t + 1));
;         *(unsigned*)(pl + (size_t)tt * PW) = pg8::cvt_pk_bf16(s0 * iv - z0, s1 * iv - z1);
;         s0 -= pg8::bf_lo(zr[tt]); s1 -= pg8::bf_hi(zr[tt]); }
.LBB0_507:
	s_or_b64 exec, exec, s[2:3]
	v_add_co_u32_e32 v14, vcc, 0x1000, v8
	s_nop 1
	v_addc_co_u32_e32 v15, vcc, 0, v9, vcc
	v_add_co_u32_e32 v16, vcc, 0x3000, v8
	s_nop 1
	v_addc_co_u32_e32 v17, vcc, 0, v9, vcc
	v_add_co_u32_e32 v18, vcc, 0x5000, v8
	s_nop 1
	v_addc_co_u32_e32 v19, vcc, 0, v9, vcc
	v_add_co_u32_e32 v20, vcc, 0x7000, v8
	s_nop 1
	v_addc_co_u32_e32 v21, vcc, 0, v9, vcc
	v_add_co_u32_e32 v22, vcc, 0x9000, v8
	s_nop 1
	v_addc_co_u32_e32 v23, vcc, 0, v9, vcc
	v_add_co_u32_e32 v24, vcc, 0xb000, v8
	s_nop 1
	v_addc_co_u32_e32 v25, vcc, 0, v9, vcc
	v_add_co_u32_e32 v26, vcc, 0xd000, v8
	s_nop 1
	v_addc_co_u32_e32 v27, vcc, 0, v9, vcc
	global_load_dword v11, v[8:9], off
	global_load_dword v13, v[14:15], off offset:3584
	global_load_dword v30, v[16:17], off offset:3072
	global_load_dword v31, v[18:19], off offset:2560
	global_load_dword v32, v[20:21], off offset:2048
	global_load_dword v33, v[22:23], off offset:1536
	global_load_dword v34, v[24:25], off offset:1024
	global_load_dword v35, v[26:27], off offset:512
	v_add_co_u32_e32 v14, vcc, 0xf000, v8
	s_nop 1
	v_addc_co_u32_e32 v15, vcc, 0, v9, vcc
	v_add_co_u32_e32 v16, vcc, 0x10000, v8
	s_nop 1
	v_addc_co_u32_e32 v17, vcc, 0, v9, vcc
	v_add_co_u32_e32 v18, vcc, 0x12000, v8
	s_nop 1
	v_addc_co_u32_e32 v19, vcc, 0, v9, vcc
	v_add_co_u32_e32 v20, vcc, 0x14000, v8
	s_nop 1
	v_addc_co_u32_e32 v21, vcc, 0, v9, vcc
	v_add_co_u32_e32 v22, vcc, 0x16000, v8
	s_nop 1
	v_addc_co_u32_e32 v23, vcc, 0, v9, vcc
	v_add_co_u32_e32 v24, vcc, 0x18000, v8
	s_nop 1
	v_addc_co_u32_e32 v25, vcc, 0, v9, vcc
	v_add_co_u32_e32 v26, vcc, 0x1a000, v8
	s_nop 1
	v_addc_co_u32_e32 v27, vcc, 0, v9, vcc
	v_add_co_u32_e32 v28, vcc, 0x1c000, v8
	s_nop 1
	v_addc_co_u32_e32 v29, vcc, 0, v9, vcc
	global_load_dword v36, v[14:15], off
	global_load_dword v37, v[16:17], off offset:3584
	global_load_dword v38, v[18:19], off offset:3072
	global_load_dword v39, v[20:21], off offset:2560
	global_load_dword v40, v[22:23], off offset:2048
	global_load_dword v41, v[24:25], off offset:1536
	global_load_dword v42, v[26:27], off offset:1024
	global_load_dword v43, v[28:29], off offset:512
	v_add_co_u32_e32 v14, vcc, 0x1e000, v8
	s_nop 1
	v_addc_co_u32_e32 v15, vcc, 0, v9, vcc
	v_add_co_u32_e32 v16, vcc, 0x1f000, v8
	s_nop 1
	v_addc_co_u32_e32 v17, vcc, 0, v9, vcc
	v_add_co_u32_e32 v18, vcc, 0x21000, v8
	s_nop 1
	v_addc_co_u32_e32 v19, vcc, 0, v9, vcc
	v_add_co_u32_e32 v20, vcc, 0x23000, v8
	s_nop 1
	v_addc_co_u32_e32 v21, vcc, 0, v9, vcc
	v_add_co_u32_e32 v22, vcc, 0x25000, v8
	s_nop 1
	v_addc_co_u32_e32 v23, vcc, 0, v9, vcc
	v_add_co_u32_e32 v24, vcc, 0x27000, v8
	s_nop 1
	v_addc_co_u32_e32 v25, vcc, 0, v9, vcc
	v_add_co_u32_e32 v26, vcc, 0x29000, v8
	s_nop 1
	v_addc_co_u32_e32 v27, vcc, 0, v9, vcc
	v_add_co_u32_e32 v28, vcc, 0x2b000, v8
	s_nop 1
	v_addc_co_u32_e32 v29, vcc, 0, v9, vcc
	global_load_dword v44, v[14:15], off
	global_load_dword v45, v[16:17], off offset:3584
	global_load_dword v46, v[18:19], off offset:3072
	global_load_dword v47, v[20:21], off offset:2560
	global_load_dword v48, v[22:23], off offset:2048
	global_load_dword v49, v[24:25], off offset:1536
	global_load_dword v50, v[26:27], off offset:1024
	s_nop 0
	global_load_dword v28, v[28:29], off offset:512
	v_add_co_u32_e32 v14, vcc, 0x2d000, v8
	s_nop 1
	v_addc_co_u32_e32 v15, vcc, 0, v9, vcc
	v_add_co_u32_e32 v16, vcc, 0x2e000, v8
	s_nop 1
	v_addc_co_u32_e32 v17, vcc, 0, v9, vcc
	v_add_co_u32_e32 v18, vcc, 0x30000, v8
	s_nop 1
	v_addc_co_u32_e32 v19, vcc, 0, v9, vcc
	v_add_co_u32_e32 v20, vcc, 0x32000, v8
	s_nop 1
	v_addc_co_u32_e32 v21, vcc, 0, v9, vcc
	v_add_co_u32_e32 v22, vcc, 0x34000, v8
	s_nop 1
	v_addc_co_u32_e32 v23, vcc, 0, v9, vcc
	v_add_co_u32_e32 v24, vcc, 0x36000, v8
	s_nop 1
	v_addc_co_u32_e32 v25, vcc, 0, v9, vcc
	v_add_co_u32_e32 v26, vcc, 0x38000, v8
	s_nop 1
	v_addc_co_u32_e32 v27, vcc, 0, v9, vcc
	v_add_co_u32_e32 v8, vcc, 0x3a000, v8
	s_nop 1
	v_addc_co_u32_e32 v9, vcc, 0, v9, vcc
	global_load_dword v14, v[14:15], off
	s_nop 0
	global_load_dword v15, v[16:17], off offset:3584
	s_nop 0
	global_load_dword v16, v[18:19], off offset:3072
	global_load_dword v17, v[20:21], off offset:2560
	s_nop 0
	global_load_dword v18, v[22:23], off offset:2048
	global_load_dword v19, v[24:25], off offset:1536
	global_load_dword v20, v[26:27], off offset:1024
	global_load_dword v21, v[8:9], off offset:512
	s_waitcnt vmcnt(32)
	v_lshlrev_b32_e32 v8, 16, v12
	v_and_b32_e32 v9, 0xffff0000, v12
	v_add_f32_e32 v12, 0, v8
	v_add_f32_e32 v22, 0, v9
	s_waitcnt vmcnt(31)
	v_lshlrev_b32_e32 v23, 16, v11
	v_and_b32_e32 v11, 0xffff0000, v11
	v_add_f32_e32 v12, v12, v23
	v_add_f32_e32 v22, v22, v11
	v_fma_f32 v24, v5, v12, -v23
	v_fma_f32 v5, v5, v22, -v11
	v_cvt_pk_bf16_f32 v5, v24, v5
	global_store_dword v[6:7], v5, off sc1
	v_sub_f32_e32 v5, v12, v8
	v_sub_f32_e32 v8, v22, v9
	s_waitcnt vmcnt(31)
	v_lshlrev_b32_e32 v9, 16, v13
	v_and_b32_e32 v12, 0xffff0000, v13
	v_add_f32_e32 v5, v5, v9
	v_add_f32_e32 v8, v8, v12
	v_fma_f32 v13, v5, 0.5, -v9
	v_fma_f32 v22, v8, 0.5, -v12
	v_cvt_pk_bf16_f32 v13, v13, v22
	v_sub_f32_e32 v5, v5, v23
	v_sub_f32_e32 v8, v8, v11
	s_waitcnt vmcnt(30)
	v_lshlrev_b32_e32 v11, 16, v30
	global_store_dword v[6:7], v13, off offset:1024 sc1
	v_and_b32_e32 v13, 0xffff0000, v30
	v_add_f32_e32 v5, v5, v11
	v_add_f32_e32 v8, v8, v13
	v_fma_f32 v22, v5, 0.5, -v11
	v_fma_f32 v23, v8, 0.5, -v13
	v_cvt_pk_bf16_f32 v22, v22, v23
	global_store_dword v[6:7], v22, off offset:2048 sc1
	v_sub_f32_e32 v5, v5, v9
	s_waitcnt vmcnt(31)
	v_lshlrev_b32_e32 v22, 16, v31
	v_sub_f32_e32 v8, v8, v12
	v_and_b32_e32 v23, 0xffff0000, v31
	v_add_f32_e32 v5, v5, v22
	v_add_f32_e32 v8, v8, v23
	v_fma_f32 v9, v5, 0.5, -v22
	v_sub_f32_e32 v5, v5, v11
	s_waitcnt vmcnt(30)
; __device__ __forceinline__ unsigned cvt_pk_bf16(float lo, float hi) { unsigned r; asm volatile("v_cvt_pk_bf16_f32 %0, %1, %2" : "=v"(r) : "v"(lo), "v"(hi)); return r; }
; __device__ __forceinline__ float bf_lo(unsigned w) { return __uint_as_float(w << 16); }
; __device__ __forceinline__ float bf_hi(unsigned w) { return __uint_as_float(w & 0xffff0000u); }
; template <int W> __device__ __forceinline__ void pool_item(const bf16* zp, bf16* pl, int t0) {
;     unsigned zr[W - 1 + 32];
; #pragma unroll
;     for (int j = 0; j < W - 1 + 32; ++j) { const int tt = j - (W - 1); zr[j] = (t0 + tt >= 0) ? *(const unsigned*)(zp + (long)tt * NIN) : 0u; }
;     float s0 = 0.f, s1 = 0.f;
; #pragma unroll
;     for (int j = 0; j < W - 1; ++j) { s0 += pg8::bf_lo(zr[j]); s1 += pg8::bf_hi(zr[j]); }
; #pragma unroll
;     for (int tt = 0; tt < 32; ++tt) { const float z0 = pg8::bf_lo(zr[W - 1 + tt]), z1 = pg8::bf_hi(zr[W - 1 + tt]); s0 += z0; s1 += z1; const int t = t0 + tt;
;         const float iv = (t + 1 >= W ? 1.0f / (float)W : 1.0f / (float)(t + 1));
;         *(unsigned*)(pl + (size_t)tt * PW) = pg8::cvt_pk_bf16(s0 * iv - z0, s1 * iv - z1);
;         s0 -= pg8::bf_lo(zr[tt]); s1 -= pg8::bf_hi(zr[tt]); }
	v_lshlrev_b32_e32 v11, 16, v32
	v_fma_f32 v12, v8, 0.5, -v23
	v_sub_f32_e32 v8, v8, v13
	v_and_b32_e32 v24, 0xffff0000, v32
	v_add_f32_e32 v5, v5, v11
	v_cvt_pk_bf16_f32 v9, v9, v12
	v_add_f32_e32 v25, v8, v24
	v_fma_f32 v8, v5, 0.5, -v11
	global_store_dword v[6:7], v9, off offset:3072 sc1
	v_fma_f32 v9, v25, 0.5, -v24
	v_cvt_pk_bf16_f32 v26, v8, v9
	v_add_co_u32_e32 v8, vcc, s14, v6
	v_sub_f32_e32 v5, v5, v22
	s_nop 0
	v_addc_co_u32_e32 v9, vcc, 0, v7, vcc
	v_add_co_u32_e32 v12, vcc, s62, v6
	v_sub_f32_e32 v22, v25, v23
	s_waitcnt vmcnt(30)
	v_lshlrev_b32_e32 v23, 16, v33
	v_and_b32_e32 v25, 0xffff0000, v33
	v_addc_co_u32_e32 v13, vcc, 0, v7, vcc
	v_add_f32_e32 v5, v5, v23
	v_add_f32_e32 v22, v22, v25
	global_store_dword v[12:13], v26, off offset:-4096 sc1
	v_fma_f32 v26, v5, 0.5, -v23
	v_fma_f32 v27, v22, 0.5, -v25
	v_sub_f32_e32 v5, v5, v11
	v_sub_f32_e32 v11, v22, v24
	s_waitcnt vmcnt(30)
	v_lshlrev_b32_e32 v22, 16, v34
	v_cvt_pk_bf16_f32 v26, v26, v27
	v_and_b32_e32 v24, 0xffff0000, v34
	v_add_f32_e32 v5, v5, v22
	global_store_dword v[8:9], v26, off offset:1024 sc1
	v_add_f32_e32 v11, v11, v24
	v_fma_f32 v26, v5, 0.5, -v22
	v_sub_f32_e32 v5, v5, v23
	s_waitcnt vmcnt(30)
	v_lshlrev_b32_e32 v23, 16, v35
	v_fma_f32 v27, v11, 0.5, -v24
	v_cvt_pk_bf16_f32 v26, v26, v27
	v_sub_f32_e32 v11, v11, v25
	v_and_b32_e32 v25, 0xffff0000, v35
	v_add_f32_e32 v5, v5, v23
	global_store_dword v[8:9], v26, off offset:2048 sc1
	v_add_f32_e32 v11, v11, v25
	v_fma_f32 v26, v5, 0.5, -v23
	v_fma_f32 v27, v11, 0.5, -v25
	v_cvt_pk_bf16_f32 v26, v26, v27
	global_store_dword v[8:9], v26, off offset:3072 sc1
	v_sub_f32_e32 v5, v5, v22
	s_waitcnt vmcnt(31)
	v_lshlrev_b32_e32 v9, 16, v36
	v_sub_f32_e32 v8, v11, v24
	v_and_b32_e32 v11, 0xffff0000, v36
	v_add_f32_e32 v5, v5, v9
	v_add_f32_e32 v8, v8, v11
	v_fma_f32 v22, v5, 0.5, -v9
	v_fma_f32 v24, v8, 0.5, -v11
	v_cvt_pk_bf16_f32 v22, v22, v24
	global_store_dword v[12:13], v22, off sc1
	v_sub_f32_e32 v5, v5, v23
	s_waitcnt vmcnt(31)
	v_lshlrev_b32_e32 v22, 16, v37
	v_sub_f32_e32 v8, v8, v25
	v_and_b32_e32 v23, 0xffff0000, v37
	v_add_f32_e32 v5, v5, v22
	v_add_f32_e32 v8, v8, v23
	v_fma_f32 v24, v5, 0.5, -v22
	v_sub_f32_e32 v5, v5, v9
	s_waitcnt vmcnt(30)
	v_lshlrev_b32_e32 v9, 16, v38
	v_fma_f32 v25, v8, 0.5, -v23
	v_cvt_pk_bf16_f32 v24, v24, v25
	v_sub_f32_e32 v8, v8, v11
	v_and_b32_e32 v11, 0xffff0000, v38
	v_add_f32_e32 v5, v5, v9
	global_store_dword v[12:13], v24, off offset:1024 sc1
	v_add_f32_e32 v8, v8, v11
	v_fma_f32 v24, v5, 0.5, -v9
	v_sub_f32_e32 v5, v5, v22
	s_waitcnt vmcnt(30)
	v_lshlrev_b32_e32 v22, 16, v39
	v_fma_f32 v25, v8, 0.5, -v11
	v_cvt_pk_bf16_f32 v24, v24, v25
	v_sub_f32_e32 v8, v8, v23
	v_and_b32_e32 v23, 0xffff0000, v39
	v_add_f32_e32 v5, v5, v22
	global_store_dword v[12:13], v24, off offset:2048 sc1
	v_add_f32_e32 v8, v8, v23
	v_fma_f32 v24, v5, 0.5, -v22
	v_fma_f32 v25, v8, 0.5, -v23
	v_cvt_pk_bf16_f32 v24, v24, v25
	v_sub_f32_e32 v5, v5, v9
	v_sub_f32_e32 v8, v8, v11
	s_waitcnt vmcnt(30)
	v_lshlrev_b32_e32 v11, 16, v40
	global_store_dword v[12:13], v24, off offset:3072 sc1
	v_and_b32_e32 v24, 0xffff0000, v40
	v_add_f32_e32 v5, v5, v11
	v_add_f32_e32 v25, v8, v24
	v_fma_f32 v8, v5, 0.5, -v11
	v_fma_f32 v9, v25, 0.5, -v24
	v_cvt_pk_bf16_f32 v26, v8, v9
	v_add_co_u32_e32 v8, vcc, s15, v6
	v_sub_f32_e32 v5, v5, v22
	s_nop 0
	v_addc_co_u32_e32 v9, vcc, 0, v7, vcc
	v_add_co_u32_e32 v12, vcc, s64, v6
	v_sub_f32_e32 v22, v25, v23
	s_waitcnt vmcnt(30)
	v_lshlrev_b32_e32 v23, 16, v41
	v_and_b32_e32 v25, 0xffff0000, v41
	v_addc_co_u32_e32 v13, vcc, 0, v7, vcc
	v_add_f32_e32 v5, v5, v23
	v_add_f32_e32 v22, v22, v25
	global_store_dword v[12:13], v26, off offset:-4096 sc1
	v_fma_f32 v26, v5, 0.5, -v23
	v_fma_f32 v27, v22, 0.5, -v25
	v_sub_f32_e32 v5, v5, v11
	v_sub_f32_e32 v11, v22, v24
	s_waitcnt vmcnt(30)
	v_lshlrev_b32_e32 v22, 16, v42
	v_cvt_pk_bf16_f32 v26, v26, v27
	v_and_b32_e32 v24, 0xffff0000, v42
	v_add_f32_e32 v5, v5, v22
	global_store_dword v[8:9], v26, off offset:1024 sc1
	v_add_f32_e32 v11, v11, v24
	v_fma_f32 v26, v5, 0.5, -v22
	v_sub_f32_e32 v5, v5, v23
	s_waitcnt vmcnt(30)
	v_lshlrev_b32_e32 v23, 16, v43
	v_fma_f32 v27, v11, 0.5, -v24
	v_cvt_pk_bf16_f32 v26, v26, v27
	v_sub_f32_e32 v11, v11, v25
	v_and_b32_e32 v25, 0xffff0000, v43
	v_add_f32_e32 v5, v5, v23
	global_store_dword v[8:9], v26, off offset:2048 sc1
	v_add_f32_e32 v11, v11, v25
	v_fma_f32 v26, v5, 0.5, -v23
	v_fma_f32 v27, v11, 0.5, -v25
	v_cvt_pk_bf16_f32 v26, v26, v27
	global_store_dword v[8:9], v26, off offset:3072 sc1
	v_sub_f32_e32 v5, v5, v22
	s_waitcnt vmcnt(31)
	v_lshlrev_b32_e32 v9, 16, v44
	v_sub_f32_e32 v8, v11, v24
	v_and_b32_e32 v11, 0xffff0000, v44
	v_add_f32_e32 v5, v5, v9
	v_add_f32_e32 v8, v8, v11
	v_fma_f32 v22, v5, 0.5, -v9
	v_fma_f32 v24, v8, 0.5, -v11
	v_cvt_pk_bf16_f32 v22, v22, v24
	global_store_dword v[12:13], v22, off sc1
	v_sub_f32_e32 v5, v5, v23
	s_waitcnt vmcnt(31)
	v_lshlrev_b32_e32 v22, 16, v45
	v_sub_f32_e32 v8, v8, v25
	v_and_b32_e32 v23, 0xffff0000, v45
	v_add_f32_e32 v5, v5, v22
	v_add_f32_e32 v8, v8, v23
	v_fma_f32 v24, v5, 0.5, -v22
	v_sub_f32_e32 v5, v5, v9
	s_waitcnt vmcnt(30)
; __device__ __forceinline__ unsigned cvt_pk_bf16(float lo, float hi) { unsigned r; asm volatile("v_cvt_pk_bf16_f32 %0, %1, %2" : "=v"(r) : "v"(lo), "v"(hi)); return r; }
; __device__ __forceinline__ float bf_lo(unsigned w) { return __uint_as_float(w << 16); }
; __device__ __forceinline__ float bf_hi(unsigned w) { return __uint_as_float(w & 0xffff0000u); }
; template <int W> __device__ __forceinline__ void pool_item(const bf16* zp, bf16* pl, int t0) {
;     ...
;     for (int tt = 0; tt < 32; ++tt) { const float z0 = pg8::bf_lo(zr[W - 1 + tt]), z1 = pg8::bf_hi(zr[W - 1 + tt]); s0 += z0; s1 += z1; const int t = t0 + tt;
;         const float iv = (t + 1 >= W ? 1.0f / (float)W : 1.0f / (float)(t + 1));
;         *(unsigned*)(pl + (size_t)tt * PW) = pg8::cvt_pk_bf16(s0 * iv - z0, s1 * iv - z1);
;         s0 -= pg8::bf_lo(zr[tt]); s1 -= pg8::bf_hi(zr[tt]); }
; __device__ __forceinline__ void attn_pool_phase(LAS unsigned char* lds, bf16* QKV, bf16* PL, const float* sinks, int G, int bid) {
;     ...
;     for (int item = bid; item < M / 64; item += G) {
	v_lshlrev_b32_e32 v9, 16, v46
	v_fma_f32 v25, v8, 0.5, -v23
	v_cvt_pk_bf16_f32 v24, v24, v25
	v_sub_f32_e32 v8, v8, v11
	v_and_b32_e32 v11, 0xffff0000, v46
	v_add_f32_e32 v5, v5, v9
	global_store_dword v[12:13], v24, off offset:1024 sc1
	v_add_f32_e32 v8, v8, v11
	v_fma_f32 v24, v5, 0.5, -v9
	v_sub_f32_e32 v5, v5, v22
	s_waitcnt vmcnt(30)
	v_lshlrev_b32_e32 v22, 16, v47
	v_fma_f32 v25, v8, 0.5, -v11
	v_cvt_pk_bf16_f32 v24, v24, v25
	v_sub_f32_e32 v8, v8, v23
	v_and_b32_e32 v23, 0xffff0000, v47
	v_add_f32_e32 v5, v5, v22
	global_store_dword v[12:13], v24, off offset:2048 sc1
	v_add_f32_e32 v8, v8, v23
	v_fma_f32 v24, v5, 0.5, -v22
	v_fma_f32 v25, v8, 0.5, -v23
	v_cvt_pk_bf16_f32 v24, v24, v25
	v_sub_f32_e32 v5, v5, v9
	v_sub_f32_e32 v8, v8, v11
	s_waitcnt vmcnt(30)
	v_lshlrev_b32_e32 v11, 16, v48
	global_store_dword v[12:13], v24, off offset:3072 sc1
	v_and_b32_e32 v24, 0xffff0000, v48
	v_add_f32_e32 v5, v5, v11
	v_add_f32_e32 v25, v8, v24
	v_fma_f32 v8, v5, 0.5, -v11
	v_fma_f32 v9, v25, 0.5, -v24
	v_cvt_pk_bf16_f32 v26, v8, v9
	v_add_co_u32_e32 v8, vcc, s17, v6
	v_sub_f32_e32 v5, v5, v22
	s_nop 0
	v_addc_co_u32_e32 v9, vcc, 0, v7, vcc
	v_add_co_u32_e32 v12, vcc, s65, v6
	v_sub_f32_e32 v22, v25, v23
	s_waitcnt vmcnt(30)
	v_lshlrev_b32_e32 v23, 16, v49
	v_and_b32_e32 v25, 0xffff0000, v49
	v_addc_co_u32_e32 v13, vcc, 0, v7, vcc
	v_add_f32_e32 v5, v5, v23
	v_add_f32_e32 v22, v22, v25
	global_store_dword v[12:13], v26, off offset:-4096 sc1
	v_fma_f32 v26, v5, 0.5, -v23
	v_fma_f32 v27, v22, 0.5, -v25
	v_sub_f32_e32 v5, v5, v11
	v_sub_f32_e32 v11, v22, v24
	s_waitcnt vmcnt(30)
	v_lshlrev_b32_e32 v22, 16, v50
	v_cvt_pk_bf16_f32 v26, v26, v27
	v_and_b32_e32 v24, 0xffff0000, v50
	v_add_f32_e32 v5, v5, v22
	global_store_dword v[8:9], v26, off offset:1024 sc1
	v_add_f32_e32 v11, v11, v24
	v_fma_f32 v26, v5, 0.5, -v22
	v_sub_f32_e32 v5, v5, v23
	s_waitcnt vmcnt(30)
	v_lshlrev_b32_e32 v23, 16, v28
	v_fma_f32 v27, v11, 0.5, -v24
	v_cvt_pk_bf16_f32 v26, v26, v27
	v_sub_f32_e32 v11, v11, v25
	v_and_b32_e32 v25, 0xffff0000, v28
	v_add_f32_e32 v5, v5, v23
	global_store_dword v[8:9], v26, off offset:2048 sc1
	v_add_f32_e32 v11, v11, v25
	v_fma_f32 v26, v5, 0.5, -v23
	v_fma_f32 v27, v11, 0.5, -v25
	v_cvt_pk_bf16_f32 v26, v26, v27
	global_store_dword v[8:9], v26, off offset:3072 sc1
	v_sub_f32_e32 v5, v5, v22
	s_waitcnt vmcnt(31)
	v_lshlrev_b32_e32 v9, 16, v14
	v_sub_f32_e32 v8, v11, v24
	v_and_b32_e32 v11, 0xffff0000, v14
	v_add_f32_e32 v5, v5, v9
	v_add_f32_e32 v8, v8, v11
	v_fma_f32 v14, v5, 0.5, -v9
	v_fma_f32 v22, v8, 0.5, -v11
	v_cvt_pk_bf16_f32 v14, v14, v22
	global_store_dword v[12:13], v14, off sc1
	v_sub_f32_e32 v5, v5, v23
	v_sub_f32_e32 v8, v8, v25
	s_waitcnt vmcnt(31)
	v_lshlrev_b32_e32 v14, 16, v15
	v_and_b32_e32 v15, 0xffff0000, v15
	v_add_f32_e32 v5, v5, v14
	v_add_f32_e32 v8, v8, v15
	v_fma_f32 v22, v5, 0.5, -v14
	v_fma_f32 v23, v8, 0.5, -v15
	v_sub_f32_e32 v5, v5, v9
	v_sub_f32_e32 v8, v8, v11
	s_waitcnt vmcnt(30)
	v_lshlrev_b32_e32 v9, 16, v16
	v_and_b32_e32 v11, 0xffff0000, v16
	v_cvt_pk_bf16_f32 v22, v22, v23
	v_add_f32_e32 v5, v5, v9
	v_add_f32_e32 v8, v8, v11
	global_store_dword v[12:13], v22, off offset:1024 sc1
	v_fma_f32 v16, v5, 0.5, -v9
	v_fma_f32 v22, v8, 0.5, -v11
	v_sub_f32_e32 v5, v5, v14
	v_sub_f32_e32 v8, v8, v15
	s_waitcnt vmcnt(30)
	v_lshlrev_b32_e32 v14, 16, v17
	v_and_b32_e32 v15, 0xffff0000, v17
	v_cvt_pk_bf16_f32 v16, v16, v22
	v_add_f32_e32 v5, v5, v14
	v_add_f32_e32 v8, v8, v15
	global_store_dword v[12:13], v16, off offset:2048 sc1
	v_fma_f32 v16, v5, 0.5, -v14
	v_fma_f32 v17, v8, 0.5, -v15
	v_sub_f32_e32 v5, v5, v9
	v_sub_f32_e32 v8, v8, v11
	s_waitcnt vmcnt(30)
	v_lshlrev_b32_e32 v11, 16, v18
	v_cvt_pk_bf16_f32 v16, v16, v17
	global_store_dword v[12:13], v16, off offset:3072 sc1
	v_and_b32_e32 v12, 0xffff0000, v18
	v_add_f32_e32 v5, v5, v11
	v_add_f32_e32 v13, v8, v12
	v_fma_f32 v8, v5, 0.5, -v11
	v_fma_f32 v9, v13, 0.5, -v12
	v_cvt_pk_bf16_f32 v16, v8, v9
	v_add_co_u32_e32 v8, vcc, s18, v6
	v_sub_f32_e32 v5, v5, v14
	v_sub_f32_e32 v13, v13, v15
	s_waitcnt vmcnt(30)
	v_lshlrev_b32_e32 v14, 16, v19
	v_and_b32_e32 v15, 0xffff0000, v19
	v_addc_co_u32_e32 v9, vcc, 0, v7, vcc
	v_add_f32_e32 v5, v5, v14
	v_add_f32_e32 v13, v13, v15
	global_store_dword v[8:9], v16, off sc1
	v_fma_f32 v16, v5, 0.5, -v14
	v_sub_f32_e32 v5, v5, v11
	v_sub_f32_e32 v11, v13, v12
	s_waitcnt vmcnt(30)
	v_lshlrev_b32_e32 v12, 16, v20
	v_fma_f32 v17, v13, 0.5, -v15
	v_and_b32_e32 v13, 0xffff0000, v20
	v_add_f32_e32 v5, v5, v12
	v_add_f32_e32 v11, v11, v13
	v_fma_f32 v12, v5, 0.5, -v12
	v_cvt_pk_bf16_f32 v16, v16, v17
	global_store_dword v[8:9], v16, off offset:1024 sc1
	v_fma_f32 v13, v11, 0.5, -v13
	v_cvt_pk_bf16_f32 v12, v12, v13
	global_store_dword v[8:9], v12, off offset:2048 sc1
	v_sub_f32_e32 v5, v5, v14
	s_waitcnt vmcnt(31)
	v_lshlrev_b32_e32 v9, 16, v21
	v_sub_f32_e32 v8, v11, v15
	v_and_b32_e32 v11, 0xffff0000, v21
	v_add_f32_e32 v5, v5, v9
	v_add_f32_e32 v8, v8, v11
	v_fma_f32 v5, v5, 0.5, -v9
	v_fma_f32 v8, v8, 0.5, -v11
	v_cvt_pk_bf16_f32 v5, v5, v8
.LBB0_508:
	v_add_co_u32_e32 v6, vcc, 0x7000, v6
	s_add_i32 s68, s68, s26
	s_nop 0
	v_addc_co_u32_e32 v7, vcc, 0, v7, vcc
	s_cmpk_lt_i32 s68, 0x200
	v_add_u32_e32 v4, s10, v4
	global_store_dword v[6:7], v5, off offset:3072 sc1
	s_cbranch_scc0 .LBB0_572

; __device__ __forceinline__ unsigned cvt_pk_bf16(float lo, float hi) { unsigned r; asm volatile("v_cvt_pk_bf16_f32 %0, %1, %2" : "=v"(r) : "v"(lo), "v"(hi)); return r; }
; __device__ __forceinline__ float bf_lo(unsigned w) { return __uint_as_float(w << 16); }
; __device__ __forceinline__ float bf_hi(unsigned w) { return __uint_as_float(w & 0xffff0000u); }
; template <int W> __device__ __forceinline__ void pool_item(const bf16* zp, bf16* pl, int t0) {
;     unsigned zr[W - 1 + 32];
; #pragma unroll
;     for (int j = 0; j < W - 1 + 32; ++j) { const int tt = j - (W - 1); zr[j] = (t0 + tt >= 0) ? *(const unsigned*)(zp + (long)tt * NIN) : 0u; }
;     float s0 = 0.f, s1 = 0.f;
; #pragma unroll
;     for (int j = 0; j < W - 1; ++j) { s0 += pg8::bf_lo(zr[j]); s1 += pg8::bf_hi(zr[j]); }
; #pragma unroll
;     for (int tt = 0; tt < 32; ++tt) { const float z0 = pg8::bf_lo(zr[W - 1 + tt]), z1 = pg8::bf_hi(zr[W - 1 + tt]); s0 += z0; s1 += z1; const int t = t0 + tt;
;         const float iv = (t + 1 >= W ? 1.0f / (float)W : 1.0f / (float)(t + 1));
;         *(unsigned*)(pl + (size_t)tt * PW) = pg8::cvt_pk_bf16(s0 * iv - z0, s1 * iv - z1);
;         s0 -= pg8::bf_lo(zr[tt]); s1 -= pg8::bf_hi(zr[tt]); }
.LBB0_542:
	s_or_b64 exec, exec, s[6:7]
	v_add_co_u32_e32 v42, vcc, s14, v8
	s_waitcnt vmcnt(0)
	v_and_b32_e32 v81, 0xffff0000, v15
	v_addc_co_u32_e32 v43, vcc, 0, v9, vcc
	v_add_co_u32_e32 v44, vcc, s15, v8
	v_lshlrev_b32_e32 v82, 16, v19
	s_nop 0
	v_addc_co_u32_e32 v45, vcc, 0, v9, vcc
	v_add_co_u32_e32 v46, vcc, s17, v8
	v_and_b32_e32 v19, 0xffff0000, v19
	s_nop 0
	v_addc_co_u32_e32 v47, vcc, 0, v9, vcc
	v_add_co_u32_e32 v48, vcc, s18, v8
	v_lshlrev_b32_e32 v83, 16, v26
	s_nop 0
	v_addc_co_u32_e32 v49, vcc, 0, v9, vcc
	v_add_co_u32_e32 v50, vcc, s19, v8
	v_and_b32_e32 v26, 0xffff0000, v26
	s_nop 0
	v_addc_co_u32_e32 v51, vcc, 0, v9, vcc
	v_add_co_u32_e32 v52, vcc, s34, v8
	v_lshlrev_b32_e32 v84, 16, v24
	s_nop 0
	v_addc_co_u32_e32 v53, vcc, 0, v9, vcc
	v_add_co_u32_e32 v54, vcc, s35, v8
	v_and_b32_e32 v24, 0xffff0000, v24
	s_nop 0
	v_addc_co_u32_e32 v55, vcc, 0, v9, vcc
	global_load_dword v41, v[8:9], off
	global_load_dword v58, v[42:43], off offset:3584
	global_load_dword v59, v[44:45], off offset:3072
	global_load_dword v60, v[46:47], off offset:2560
	global_load_dword v61, v[48:49], off offset:2048
	global_load_dword v62, v[50:51], off offset:1536
	global_load_dword v63, v[52:53], off offset:1024
	global_load_dword v64, v[54:55], off offset:512
	v_add_co_u32_e32 v42, vcc, s36, v8
	v_lshlrev_b32_e32 v85, 16, v31
	s_nop 0
	v_addc_co_u32_e32 v43, vcc, 0, v9, vcc
	v_add_co_u32_e32 v44, vcc, s37, v8
	v_and_b32_e32 v31, 0xffff0000, v31
	s_nop 0
	v_addc_co_u32_e32 v45, vcc, 0, v9, vcc
	v_add_co_u32_e32 v46, vcc, s38, v8
	v_lshlrev_b32_e32 v86, 16, v29
	s_nop 0
	v_addc_co_u32_e32 v47, vcc, 0, v9, vcc
	v_add_co_u32_e32 v48, vcc, s39, v8
	v_and_b32_e32 v29, 0xffff0000, v29
	s_nop 0
	v_addc_co_u32_e32 v49, vcc, 0, v9, vcc
	v_add_co_u32_e32 v50, vcc, s40, v8
	v_lshlrev_b32_e32 v87, 16, v35
	s_nop 0
	v_addc_co_u32_e32 v51, vcc, 0, v9, vcc
	v_add_co_u32_e32 v52, vcc, s41, v8
	v_and_b32_e32 v35, 0xffff0000, v35
	s_nop 0
	v_addc_co_u32_e32 v53, vcc, 0, v9, vcc
	v_add_co_u32_e32 v54, vcc, s42, v8
	v_lshlrev_b32_e32 v88, 16, v33
	s_nop 0
	v_addc_co_u32_e32 v55, vcc, 0, v9, vcc
	v_add_co_u32_e32 v56, vcc, s43, v8
	v_and_b32_e32 v33, 0xffff0000, v33
	s_nop 0
	v_addc_co_u32_e32 v57, vcc, 0, v9, vcc
	global_load_dword v65, v[42:43], off
	global_load_dword v66, v[44:45], off offset:3584
	global_load_dword v67, v[46:47], off offset:3072
	global_load_dword v68, v[48:49], off offset:2560
	global_load_dword v69, v[50:51], off offset:2048
	global_load_dword v70, v[52:53], off offset:1536
	global_load_dword v71, v[54:55], off offset:1024
	global_load_dword v72, v[56:57], off offset:512
	v_add_co_u32_e32 v42, vcc, s44, v8
	v_lshlrev_b32_e32 v89, 16, v39
	s_nop 0
	v_addc_co_u32_e32 v43, vcc, 0, v9, vcc
	v_add_co_u32_e32 v44, vcc, s45, v8
	v_and_b32_e32 v39, 0xffff0000, v39
	s_nop 0
	v_addc_co_u32_e32 v45, vcc, 0, v9, vcc
	v_add_co_u32_e32 v46, vcc, s46, v8
	s_mov_b64 s[6:7], 0
	s_nop 0
	v_addc_co_u32_e32 v47, vcc, 0, v9, vcc
	v_add_co_u32_e32 v48, vcc, s47, v8
	s_waitcnt vmcnt(15)
	v_lshlrev_b32_e32 v90, 16, v41
	v_addc_co_u32_e32 v49, vcc, 0, v9, vcc
	v_add_co_u32_e32 v50, vcc, s48, v8
	v_and_b32_e32 v41, 0xffff0000, v41
	s_nop 0
	v_addc_co_u32_e32 v51, vcc, 0, v9, vcc
	v_add_co_u32_e32 v52, vcc, s49, v8
	s_nop 1
	v_addc_co_u32_e32 v53, vcc, 0, v9, vcc
	v_add_co_u32_e32 v54, vcc, s52, v8
	s_nop 1
	v_addc_co_u32_e32 v55, vcc, 0, v9, vcc
	v_add_co_u32_e32 v56, vcc, s53, v8
	s_nop 1
	v_addc_co_u32_e32 v57, vcc, 0, v9, vcc
	global_load_dword v73, v[42:43], off
	global_load_dword v74, v[44:45], off offset:3584
	global_load_dword v75, v[46:47], off offset:3072
	global_load_dword v76, v[48:49], off offset:2560
	global_load_dword v77, v[50:51], off offset:2048
	global_load_dword v78, v[52:53], off offset:1536
	global_load_dword v79, v[54:55], off offset:1024
	global_load_dword v80, v[56:57], off offset:512
	v_add_co_u32_e32 v42, vcc, s54, v8
	s_nop 1
	v_addc_co_u32_e32 v43, vcc, 0, v9, vcc
	v_add_co_u32_e32 v44, vcc, s55, v8
	s_nop 1
	v_addc_co_u32_e32 v45, vcc, 0, v9, vcc
	v_add_co_u32_e32 v46, vcc, s56, v8
	s_nop 1
	v_addc_co_u32_e32 v47, vcc, 0, v9, vcc
	v_add_co_u32_e32 v48, vcc, s57, v8
	s_nop 1
	v_addc_co_u32_e32 v49, vcc, 0, v9, vcc
	v_add_co_u32_e32 v50, vcc, s58, v8
	s_nop 1
	v_addc_co_u32_e32 v51, vcc, 0, v9, vcc
	v_add_co_u32_e32 v52, vcc, s59, v8
	s_nop 1
	v_addc_co_u32_e32 v53, vcc, 0, v9, vcc
	v_add_co_u32_e32 v54, vcc, s60, v8
	s_nop 1
	v_addc_co_u32_e32 v55, vcc, 0, v9, vcc
	v_add_co_u32_e32 v56, vcc, s61, v8
	s_nop 1
	v_addc_co_u32_e32 v57, vcc, 0, v9, vcc
	global_load_dword v42, v[42:43], off
	s_nop 0
	global_load_dword v43, v[44:45], off offset:3584
	s_nop 0
	global_load_dword v44, v[46:47], off offset:3072
	global_load_dword v45, v[48:49], off offset:2560
	s_nop 0
	global_load_dword v46, v[50:51], off offset:2048
	global_load_dword v47, v[52:53], off offset:1536
	global_load_dword v48, v[54:55], off offset:1024
	global_load_dword v49, v[56:57], off offset:512
	v_lshlrev_b32_e32 v50, 16, v12
	v_and_b32_e32 v12, 0xffff0000, v12
	v_add_f32_e32 v51, 0, v50
	v_add_f32_e32 v52, 0, v12
	v_lshlrev_b32_e32 v53, 16, v5
	v_and_b32_e32 v5, 0xffff0000, v5
	v_add_f32_e32 v51, v51, v53
	v_add_f32_e32 v52, v52, v5
	v_lshlrev_b32_e32 v54, 16, v14
	v_and_b32_e32 v14, 0xffff0000, v14
	v_add_f32_e32 v51, v51, v54
	v_add_f32_e32 v52, v52, v14
	v_lshlrev_b32_e32 v55, 16, v13
	v_and_b32_e32 v13, 0xffff0000, v13
	v_add_f32_e32 v51, v51, v55
	v_add_f32_e32 v52, v52, v13
	v_lshlrev_b32_e32 v56, 16, v17
	v_and_b32_e32 v17, 0xffff0000, v17
	v_add_f32_e32 v51, v51, v56
	v_add_f32_e32 v52, v52, v17
	v_lshlrev_b32_e32 v57, 16, v15
	v_add_f32_e32 v51, v51, v57
	v_add_f32_e32 v15, v52, v81
	v_lshlrev_b32_e32 v52, 16, v21
	v_and_b32_e32 v21, 0xffff0000, v21
	v_add_f32_e32 v51, v51, v52
	v_add_f32_e32 v15, v15, v21
	v_add_f32_e32 v51, v51, v82
	v_add_f32_e32 v15, v15, v19
	v_add_f32_e32 v51, v51, v83
	v_add_f32_e32 v15, v15, v26
	v_add_f32_e32 v51, v51, v84
	v_add_f32_e32 v15, v15, v24
	v_add_f32_e32 v51, v51, v85
	v_add_f32_e32 v15, v15, v31
	v_add_f32_e32 v51, v51, v86
	v_add_f32_e32 v15, v15, v29
	v_add_f32_e32 v51, v51, v87
	v_add_f32_e32 v15, v15, v35
	v_add_f32_e32 v51, v51, v88
	v_add_f32_e32 v15, v15, v33
	v_add_f32_e32 v51, v51, v89
	v_add_f32_e32 v15, v15, v39
	v_add_f32_e32 v51, v51, v90
	v_add_f32_e32 v15, v15, v41
	v_fma_f32 v91, v40, v51, -v90
	v_fma_f32 v40, v40, v15, -v41
	v_cvt_pk_bf16_f32 v40, v91, v40
	global_store_dword v[6:7], v40, off sc1
	v_sub_f32_e32 v40, v51, v50
	v_sub_f32_e32 v12, v15, v12
	s_waitcnt vmcnt(31)
; __device__ __forceinline__ unsigned cvt_pk_bf16(float lo, float hi) { unsigned r; asm volatile("v_cvt_pk_bf16_f32 %0, %1, %2" : "=v"(r) : "v"(lo), "v"(hi)); return r; }
; __device__ __forceinline__ float bf_lo(unsigned w) { return __uint_as_float(w << 16); }
; __device__ __forceinline__ float bf_hi(unsigned w) { return __uint_as_float(w & 0xffff0000u); }
; template <int W> __device__ __forceinline__ void pool_item(const bf16* zp, bf16* pl, int t0) {
;     unsigned zr[W - 1 + 32];
; #pragma unroll
;     for (int j = 0; j < W - 1 + 32; ++j) { const int tt = j - (W - 1); zr[j] = (t0 + tt >= 0) ? *(const unsigned*)(zp + (long)tt * NIN) : 0u; }
;     float s0 = 0.f, s1 = 0.f;
; #pragma unroll
;     for (int j = 0; j < W - 1; ++j) { s0 += pg8::bf_lo(zr[j]); s1 += pg8::bf_hi(zr[j]); }
; #pragma unroll
;     for (int tt = 0; tt < 32; ++tt) { const float z0 = pg8::bf_lo(zr[W - 1 + tt]), z1 = pg8::bf_hi(zr[W - 1 + tt]); s0 += z0; s1 += z1; const int t = t0 + tt;
;         const float iv = (t + 1 >= W ? 1.0f / (float)W : 1.0f / (float)(t + 1));
;         *(unsigned*)(pl + (size_t)tt * PW) = pg8::cvt_pk_bf16(s0 * iv - z0, s1 * iv - z1);
;         s0 -= pg8::bf_lo(zr[tt]); s1 -= pg8::bf_hi(zr[tt]); }
	v_lshlrev_b32_e32 v50, 16, v58
	v_and_b32_e32 v51, 0xffff0000, v58
	v_add_f32_e32 v15, v40, v50
	v_add_f32_e32 v12, v12, v51
	v_fma_f32 v40, v38, v15, -v50
	v_fma_f32 v38, v38, v12, -v51
	v_cvt_pk_bf16_f32 v38, v40, v38
	global_store_dword v[6:7], v38, off offset:1024 sc1
	v_sub_f32_e32 v15, v15, v53
	v_sub_f32_e32 v5, v12, v5
	s_waitcnt vmcnt(31)
	v_lshlrev_b32_e32 v38, 16, v59
	v_and_b32_e32 v40, 0xffff0000, v59
	v_add_f32_e32 v12, v15, v38
	v_add_f32_e32 v5, v5, v40
	v_fma_f32 v15, v37, v12, -v38
	v_fma_f32 v37, v37, v5, -v40
	v_cvt_pk_bf16_f32 v15, v15, v37
	v_sub_f32_e32 v12, v12, v54
	v_sub_f32_e32 v5, v5, v14
	s_waitcnt vmcnt(30)
	v_lshlrev_b32_e32 v37, 16, v60
	v_and_b32_e32 v53, 0xffff0000, v60
	v_add_f32_e32 v12, v12, v37
	v_add_f32_e32 v5, v5, v53
	global_store_dword v[6:7], v15, off offset:2048 sc1
	v_fma_f32 v14, v36, v12, -v37
	v_fma_f32 v15, v36, v5, -v53
	v_sub_f32_e32 v12, v12, v55
	s_waitcnt vmcnt(30)
	v_lshlrev_b32_e32 v36, 16, v61
	v_sub_f32_e32 v5, v5, v13
	v_and_b32_e32 v54, 0xffff0000, v61
	v_add_f32_e32 v55, v12, v36
	v_add_f32_e32 v5, v5, v54
	v_fma_f32 v12, v34, v55, -v36
	v_cvt_pk_bf16_f32 v14, v14, v15
	global_store_dword v[6:7], v14, off offset:3072 sc1
	v_fma_f32 v13, v34, v5, -v54
	v_cvt_pk_bf16_f32 v34, v12, v13
	v_add_co_u32_e32 v12, vcc, s14, v6
	v_sub_f32_e32 v5, v5, v17
	s_nop 0
	v_addc_co_u32_e32 v13, vcc, 0, v7, vcc
	v_add_co_u32_e32 v14, vcc, s62, v6
	s_waitcnt vmcnt(30)
	v_lshlrev_b32_e32 v17, 16, v62
	v_addc_co_u32_e32 v15, vcc, 0, v7, vcc
	global_store_dword v[14:15], v34, off offset:-4096 sc1
	v_sub_f32_e32 v34, v55, v56
	v_and_b32_e32 v55, 0xffff0000, v62
	v_add_f32_e32 v34, v34, v17
	v_add_f32_e32 v5, v5, v55
	v_fma_f32 v56, v32, v34, -v17
	v_fma_f32 v32, v32, v5, -v55
	v_cvt_pk_bf16_f32 v32, v56, v32
	global_store_dword v[12:13], v32, off offset:1024 sc1
	v_sub_f32_e32 v32, v34, v57
	v_sub_f32_e32 v5, v5, v81
	s_waitcnt vmcnt(31)
	v_lshlrev_b32_e32 v34, 16, v63
	v_and_b32_e32 v56, 0xffff0000, v63
	v_add_f32_e32 v32, v32, v34
	v_add_f32_e32 v5, v5, v56
	v_fma_f32 v57, v30, v32, -v34
	v_fma_f32 v30, v30, v5, -v56
	v_cvt_pk_bf16_f32 v30, v57, v30
	global_store_dword v[12:13], v30, off offset:2048 sc1
	v_sub_f32_e32 v30, v32, v52
	v_sub_f32_e32 v5, v5, v21
	s_waitcnt vmcnt(31)
	v_lshlrev_b32_e32 v21, 16, v64
	v_and_b32_e32 v32, 0xffff0000, v64
	v_add_f32_e32 v30, v30, v21
	v_add_f32_e32 v5, v5, v32
	v_fma_f32 v52, v28, v30, -v21
	v_fma_f32 v28, v28, v5, -v32
	v_cvt_pk_bf16_f32 v28, v52, v28
	global_store_dword v[12:13], v28, off offset:3072 sc1
	v_sub_f32_e32 v12, v30, v82
	v_sub_f32_e32 v5, v5, v19
	s_waitcnt vmcnt(31)
	v_lshlrev_b32_e32 v19, 16, v65
	v_and_b32_e32 v28, 0xffff0000, v65
	v_add_f32_e32 v12, v12, v19
	v_add_f32_e32 v5, v5, v28
	v_fma_f32 v13, v27, v12, -v19
	v_fma_f32 v27, v27, v5, -v28
	v_cvt_pk_bf16_f32 v13, v13, v27
	v_sub_f32_e32 v12, v12, v83
	v_sub_f32_e32 v5, v5, v26
	s_waitcnt vmcnt(30)
	v_lshlrev_b32_e32 v26, 16, v66
	v_and_b32_e32 v27, 0xffff0000, v66
	v_add_f32_e32 v12, v12, v26
	v_add_f32_e32 v5, v5, v27
	global_store_dword v[14:15], v13, off sc1
	v_fma_f32 v13, v25, v12, -v26
	v_fma_f32 v25, v25, v5, -v27
	v_cvt_pk_bf16_f32 v13, v13, v25
	v_sub_f32_e32 v12, v12, v84
	v_sub_f32_e32 v5, v5, v24
	s_waitcnt vmcnt(30)
	v_lshlrev_b32_e32 v24, 16, v67
	v_and_b32_e32 v25, 0xffff0000, v67
	v_add_f32_e32 v12, v12, v24
	v_add_f32_e32 v5, v5, v25
	global_store_dword v[14:15], v13, off offset:1024 sc1
	v_fma_f32 v13, v23, v12, -v24
	v_fma_f32 v23, v23, v5, -v25
	v_cvt_pk_bf16_f32 v13, v13, v23
	v_sub_f32_e32 v12, v12, v85
	v_sub_f32_e32 v5, v5, v31
	s_waitcnt vmcnt(30)
	v_lshlrev_b32_e32 v23, 16, v68
	v_and_b32_e32 v30, 0xffff0000, v68
	v_add_f32_e32 v12, v12, v23
	v_add_f32_e32 v5, v5, v30
	global_store_dword v[14:15], v13, off offset:2048 sc1
	v_fma_f32 v13, v22, v12, -v23
	v_fma_f32 v22, v22, v5, -v30
	v_cvt_pk_bf16_f32 v13, v13, v22
	v_sub_f32_e32 v12, v12, v86
	s_waitcnt vmcnt(30)
	v_lshlrev_b32_e32 v22, 16, v69
	v_sub_f32_e32 v5, v5, v29
	v_and_b32_e32 v29, 0xffff0000, v69
	v_add_f32_e32 v31, v12, v22
	v_add_f32_e32 v5, v5, v29
	v_fma_f32 v12, v20, v31, -v22
	global_store_dword v[14:15], v13, off offset:3072 sc1
	v_fma_f32 v13, v20, v5, -v29
	v_cvt_pk_bf16_f32 v20, v12, v13
	v_add_co_u32_e32 v12, vcc, s15, v6
	v_sub_f32_e32 v5, v5, v35
	s_nop 0
	v_addc_co_u32_e32 v13, vcc, 0, v7, vcc
	v_add_co_u32_e32 v14, vcc, s64, v6
	v_sub_f32_e32 v31, v31, v87
	s_nop 0
	v_addc_co_u32_e32 v15, vcc, 0, v7, vcc
	global_store_dword v[14:15], v20, off offset:-4096 sc1
	s_waitcnt vmcnt(31)
	v_and_b32_e32 v20, 0xffff0000, v70
	v_lshlrev_b32_e32 v35, 16, v70
	v_add_f32_e32 v5, v5, v20
	v_add_f32_e32 v31, v31, v35
	v_fma_f32 v52, v18, v31, -v35
	v_fma_f32 v18, v18, v5, -v20
	v_cvt_pk_bf16_f32 v18, v52, v18
	global_store_dword v[12:13], v18, off offset:1024 sc1
	v_sub_f32_e32 v18, v31, v88
	v_sub_f32_e32 v5, v5, v33
	s_waitcnt vmcnt(31)
	v_lshlrev_b32_e32 v31, 16, v71
	v_and_b32_e32 v33, 0xffff0000, v71
	v_add_f32_e32 v18, v18, v31
	v_add_f32_e32 v5, v5, v33
	v_fma_f32 v52, v16, v18, -v31
	v_fma_f32 v16, v16, v5, -v33
	v_cvt_pk_bf16_f32 v16, v52, v16
	global_store_dword v[12:13], v16, off offset:2048 sc1
	s_waitcnt vmcnt(31)
	v_lshlrev_b32_e32 v16, 16, v72
	v_sub_f32_e32 v18, v18, v89
	v_and_b32_e32 v52, 0xffff0000, v72
	v_sub_f32_e32 v5, v5, v39
	v_add_f32_e32 v18, v18, v16
	v_add_f32_e32 v5, v5, v52
	v_fma_f32 v39, v18, s63, -v16
	v_fma_f32 v57, v5, s63, -v52
	v_cvt_pk_bf16_f32 v39, v39, v57
	global_store_dword v[12:13], v39, off offset:3072 sc1
	v_sub_f32_e32 v5, v5, v41
	s_waitcnt vmcnt(31)
; __device__ __forceinline__ unsigned cvt_pk_bf16(float lo, float hi) { unsigned r; asm volatile("v_cvt_pk_bf16_f32 %0, %1, %2" : "=v"(r) : "v"(lo), "v"(hi)); return r; }
; __device__ __forceinline__ float bf_lo(unsigned w) { return __uint_as_float(w << 16); }
; __device__ __forceinline__ float bf_hi(unsigned w) { return __uint_as_float(w & 0xffff0000u); }
; template <int W> __device__ __forceinline__ void pool_item(const bf16* zp, bf16* pl, int t0) {
;     unsigned zr[W - 1 + 32];
; #pragma unroll
;     for (int j = 0; j < W - 1 + 32; ++j) { const int tt = j - (W - 1); zr[j] = (t0 + tt >= 0) ? *(const unsigned*)(zp + (long)tt * NIN) : 0u; }
;     float s0 = 0.f, s1 = 0.f;
; #pragma unroll
;     for (int j = 0; j < W - 1; ++j) { s0 += pg8::bf_lo(zr[j]); s1 += pg8::bf_hi(zr[j]); }
; #pragma unroll
;     for (int tt = 0; tt < 32; ++tt) { const float z0 = pg8::bf_lo(zr[W - 1 + tt]), z1 = pg8::bf_hi(zr[W - 1 + tt]); s0 += z0; s1 += z1; const int t = t0 + tt;
;         const float iv = (t + 1 >= W ? 1.0f / (float)W : 1.0f / (float)(t + 1));
;         *(unsigned*)(pl + (size_t)tt * PW) = pg8::cvt_pk_bf16(s0 * iv - z0, s1 * iv - z1);
;         s0 -= pg8::bf_lo(zr[tt]); s1 -= pg8::bf_hi(zr[tt]); }
	v_and_b32_e32 v12, 0xffff0000, v73
	v_add_f32_e32 v5, v5, v12
	v_sub_f32_e32 v13, v18, v90
	v_lshlrev_b32_e32 v18, 16, v73
	v_add_f32_e32 v13, v13, v18
	v_fma_f32 v12, v5, s63, -v12
	v_fma_f32 v18, v13, s63, -v18
	v_cvt_pk_bf16_f32 v12, v18, v12
	global_store_dword v[14:15], v12, off sc1
	v_sub_f32_e32 v5, v5, v51
	s_waitcnt vmcnt(31)
	v_and_b32_e32 v12, 0xffff0000, v74
	v_add_f32_e32 v5, v5, v12
	v_sub_f32_e32 v13, v13, v50
	v_lshlrev_b32_e32 v18, 16, v74
	v_add_f32_e32 v13, v13, v18
	v_fma_f32 v12, v5, s63, -v12
	v_fma_f32 v18, v13, s63, -v18
	v_cvt_pk_bf16_f32 v12, v18, v12
	global_store_dword v[14:15], v12, off offset:1024 sc1
	v_sub_f32_e32 v5, v5, v40
	s_waitcnt vmcnt(31)
	v_and_b32_e32 v12, 0xffff0000, v75
	v_add_f32_e32 v5, v5, v12
	v_sub_f32_e32 v13, v13, v38
	v_lshlrev_b32_e32 v18, 16, v75
	v_add_f32_e32 v13, v13, v18
	v_fma_f32 v12, v5, s63, -v12
	v_fma_f32 v18, v13, s63, -v18
	v_cvt_pk_bf16_f32 v12, v18, v12
	global_store_dword v[14:15], v12, off offset:2048 sc1
	v_sub_f32_e32 v5, v5, v53
	s_waitcnt vmcnt(31)
	v_and_b32_e32 v12, 0xffff0000, v76
	v_add_f32_e32 v5, v5, v12
	v_sub_f32_e32 v13, v13, v37
	v_lshlrev_b32_e32 v18, 16, v76
	v_add_f32_e32 v13, v13, v18
	v_fma_f32 v12, v5, s63, -v12
	v_fma_f32 v18, v13, s63, -v18
	v_cvt_pk_bf16_f32 v12, v18, v12
	global_store_dword v[14:15], v12, off offset:3072 sc1
	v_sub_f32_e32 v5, v5, v54
	s_waitcnt vmcnt(31)
	v_and_b32_e32 v12, 0xffff0000, v77
	v_add_f32_e32 v5, v5, v12
	v_sub_f32_e32 v13, v13, v36
	v_lshlrev_b32_e32 v14, 16, v77
	v_add_f32_e32 v18, v13, v14
	v_fma_f32 v12, v5, s63, -v12
	v_fma_f32 v13, v18, s63, -v14
	v_cvt_pk_bf16_f32 v36, v13, v12
	v_add_co_u32_e32 v12, vcc, s17, v6
	v_sub_f32_e32 v17, v18, v17
	s_nop 0
	v_addc_co_u32_e32 v13, vcc, 0, v7, vcc
	v_add_co_u32_e32 v14, vcc, s65, v6
	s_waitcnt vmcnt(30)
	v_lshlrev_b32_e32 v18, 16, v78
	v_addc_co_u32_e32 v15, vcc, 0, v7, vcc
	global_store_dword v[14:15], v36, off offset:-4096 sc1
	v_sub_f32_e32 v5, v5, v55
	v_and_b32_e32 v36, 0xffff0000, v78
	v_add_f32_e32 v17, v17, v18
	v_add_f32_e32 v5, v5, v36
	v_fma_f32 v18, v17, s63, -v18
	v_fma_f32 v36, v5, s63, -v36
	v_cvt_pk_bf16_f32 v18, v18, v36
	global_store_dword v[12:13], v18, off offset:1024 sc1
	v_sub_f32_e32 v5, v5, v56
	s_waitcnt vmcnt(31)
	v_and_b32_e32 v18, 0xffff0000, v79
	v_add_f32_e32 v5, v5, v18
	v_sub_f32_e32 v17, v17, v34
	v_lshlrev_b32_e32 v34, 16, v79
	v_add_f32_e32 v17, v17, v34
	v_fma_f32 v18, v5, s63, -v18
	v_fma_f32 v34, v17, s63, -v34
	v_cvt_pk_bf16_f32 v18, v34, v18
	global_store_dword v[12:13], v18, off offset:2048 sc1
	v_sub_f32_e32 v5, v5, v32
	s_waitcnt vmcnt(31)
	v_and_b32_e32 v18, 0xffff0000, v80
	v_add_f32_e32 v5, v5, v18
	v_sub_f32_e32 v17, v17, v21
	v_lshlrev_b32_e32 v21, 16, v80
	v_add_f32_e32 v17, v17, v21
	v_fma_f32 v18, v5, s63, -v18
	v_fma_f32 v21, v17, s63, -v21
	v_cvt_pk_bf16_f32 v18, v21, v18
	global_store_dword v[12:13], v18, off offset:3072 sc1
	v_sub_f32_e32 v5, v5, v28
	s_waitcnt vmcnt(31)
	v_and_b32_e32 v12, 0xffff0000, v42
	v_add_f32_e32 v5, v5, v12
	v_sub_f32_e32 v13, v17, v19
	v_lshlrev_b32_e32 v17, 16, v42
	v_add_f32_e32 v13, v13, v17
	v_fma_f32 v12, v5, s63, -v12
	v_fma_f32 v17, v13, s63, -v17
	v_cvt_pk_bf16_f32 v12, v17, v12
	global_store_dword v[14:15], v12, off sc1
	v_sub_f32_e32 v5, v5, v27
	s_waitcnt vmcnt(31)
	v_and_b32_e32 v12, 0xffff0000, v43
	v_add_f32_e32 v5, v5, v12
	v_sub_f32_e32 v13, v13, v26
	v_lshlrev_b32_e32 v17, 16, v43
	v_add_f32_e32 v13, v13, v17
	v_fma_f32 v12, v5, s63, -v12
	v_fma_f32 v17, v13, s63, -v17
	v_cvt_pk_bf16_f32 v12, v17, v12
	global_store_dword v[14:15], v12, off offset:1024 sc1
	v_sub_f32_e32 v5, v5, v25
	s_waitcnt vmcnt(31)
	v_and_b32_e32 v12, 0xffff0000, v44
	v_add_f32_e32 v5, v5, v12
	v_sub_f32_e32 v13, v13, v24
	v_lshlrev_b32_e32 v17, 16, v44
	v_add_f32_e32 v13, v13, v17
	v_fma_f32 v12, v5, s63, -v12
	v_fma_f32 v17, v13, s63, -v17
	v_cvt_pk_bf16_f32 v12, v17, v12
	global_store_dword v[14:15], v12, off offset:2048 sc1
	v_sub_f32_e32 v5, v5, v30
	s_waitcnt vmcnt(31)
	v_and_b32_e32 v12, 0xffff0000, v45
	v_add_f32_e32 v5, v5, v12
	v_sub_f32_e32 v13, v13, v23
	v_lshlrev_b32_e32 v17, 16, v45
	v_add_f32_e32 v13, v13, v17
	v_fma_f32 v12, v5, s63, -v12
	v_fma_f32 v17, v13, s63, -v17
	v_cvt_pk_bf16_f32 v12, v17, v12
	global_store_dword v[14:15], v12, off offset:3072 sc1
	v_sub_f32_e32 v5, v5, v29
	s_waitcnt vmcnt(31)
	v_and_b32_e32 v12, 0xffff0000, v46
	v_add_f32_e32 v5, v5, v12
	v_sub_f32_e32 v13, v13, v22
	v_lshlrev_b32_e32 v14, 16, v46
	v_add_f32_e32 v15, v13, v14
	v_fma_f32 v12, v5, s63, -v12
	v_fma_f32 v13, v15, s63, -v14
	v_cvt_pk_bf16_f32 v14, v13, v12
	v_add_co_u32_e32 v12, vcc, s18, v6
	v_sub_f32_e32 v5, v5, v20
	s_nop 0
	v_addc_co_u32_e32 v13, vcc, 0, v7, vcc
	global_store_dword v[12:13], v14, off sc1
	s_waitcnt vmcnt(31)
	v_and_b32_e32 v14, 0xffff0000, v47
	v_add_f32_e32 v5, v5, v14
	v_sub_f32_e32 v15, v15, v35
	v_lshlrev_b32_e32 v17, 16, v47
	v_add_f32_e32 v15, v15, v17
	v_fma_f32 v14, v5, s63, -v14
	v_fma_f32 v17, v15, s63, -v17
	v_cvt_pk_bf16_f32 v14, v17, v14
	global_store_dword v[12:13], v14, off offset:1024 sc1
	v_sub_f32_e32 v5, v5, v33
	s_waitcnt vmcnt(31)
	v_and_b32_e32 v14, 0xffff0000, v48
	v_add_f32_e32 v5, v5, v14
	v_sub_f32_e32 v15, v15, v31
	v_lshlrev_b32_e32 v17, 16, v48
	v_add_f32_e32 v15, v15, v17
	v_fma_f32 v14, v5, s63, -v14
	v_fma_f32 v17, v15, s63, -v17
	v_cvt_pk_bf16_f32 v14, v17, v14
	global_store_dword v[12:13], v14, off offset:2048 sc1
	v_sub_f32_e32 v5, v5, v52
	s_waitcnt vmcnt(31)
	v_and_b32_e32 v12, 0xffff0000, v49
	v_add_f32_e32 v5, v5, v12
	v_sub_f32_e32 v13, v15, v16
	v_lshlrev_b32_e32 v14, 16, v49
	v_add_f32_e32 v13, v13, v14
	v_fma_f32 v5, v5, s63, -v12
	v_fma_f32 v13, v13, s63, -v14
	v_cvt_pk_bf16_f32 v5, v13, v5

; __device__ __forceinline__ unsigned cvt_pk_bf16(float lo, float hi) { unsigned r; asm volatile("v_cvt_pk_bf16_f32 %0, %1, %2" : "=v"(r) : "v"(lo), "v"(hi)); return r; }
; __device__ __forceinline__ float bf_lo(unsigned w) { return __uint_as_float(w << 16); }
; __device__ __forceinline__ float bf_hi(unsigned w) { return __uint_as_float(w & 0xffff0000u); }
; template <int W> __device__ __forceinline__ void pool_item(const bf16* zp, bf16* pl, int t0) {
;     unsigned zr[W - 1 + 32];
; #pragma unroll
;     for (int j = 0; j < W - 1 + 32; ++j) { const int tt = j - (W - 1); zr[j] = (t0 + tt >= 0) ? *(const unsigned*)(zp + (long)tt * NIN) : 0u; }
;     float s0 = 0.f, s1 = 0.f;
; #pragma unroll
;     for (int j = 0; j < W - 1; ++j) { s0 += pg8::bf_lo(zr[j]); s1 += pg8::bf_hi(zr[j]); }
; #pragma unroll
;     for (int tt = 0; tt < 32; ++tt) { const float z0 = pg8::bf_lo(zr[W - 1 + tt]), z1 = pg8::bf_hi(zr[W - 1 + tt]); s0 += z0; s1 += z1; const int t = t0 + tt;
;         const float iv = (t + 1 >= W ? 1.0f / (float)W : 1.0f / (float)(t + 1));
;         *(unsigned*)(pl + (size_t)tt * PW) = pg8::cvt_pk_bf16(s0 * iv - z0, s1 * iv - z1);
;         s0 -= pg8::bf_lo(zr[tt]); s1 -= pg8::bf_hi(zr[tt]); }
.LBB0_558:
	s_or_b64 exec, exec, s[6:7]
	v_add_co_u32_e32 v26, vcc, 0x1000, v8
	s_waitcnt vmcnt(0)
	v_and_b32_e32 v65, 0xffff0000, v18
	v_addc_co_u32_e32 v27, vcc, 0, v9, vcc
	v_add_co_u32_e32 v28, vcc, 0x3000, v8
	v_lshlrev_b32_e32 v66, 16, v23
	s_nop 0
	v_addc_co_u32_e32 v29, vcc, 0, v9, vcc
	v_add_co_u32_e32 v30, vcc, 0x5000, v8
	v_and_b32_e32 v23, 0xffff0000, v23
	s_nop 0
	v_addc_co_u32_e32 v31, vcc, 0, v9, vcc
	v_add_co_u32_e32 v32, vcc, 0x7000, v8
	s_nop 1
	v_addc_co_u32_e32 v33, vcc, 0, v9, vcc
	v_add_co_u32_e32 v34, vcc, 0x9000, v8
	s_nop 1
	v_addc_co_u32_e32 v35, vcc, 0, v9, vcc
	v_add_co_u32_e32 v36, vcc, 0xb000, v8
	s_nop 1
	v_addc_co_u32_e32 v37, vcc, 0, v9, vcc
	v_add_co_u32_e32 v38, vcc, 0xd000, v8
	s_nop 1
	v_addc_co_u32_e32 v39, vcc, 0, v9, vcc
	global_load_dword v25, v[8:9], off
	global_load_dword v42, v[26:27], off offset:3584
	global_load_dword v43, v[28:29], off offset:3072
	global_load_dword v44, v[30:31], off offset:2560
	global_load_dword v45, v[32:33], off offset:2048
	global_load_dword v46, v[34:35], off offset:1536
	global_load_dword v47, v[36:37], off offset:1024
	global_load_dword v48, v[38:39], off offset:512
	v_add_co_u32_e32 v26, vcc, 0xf000, v8
	s_nop 1
	v_addc_co_u32_e32 v27, vcc, 0, v9, vcc
	v_add_co_u32_e32 v28, vcc, 0x10000, v8
	s_nop 1
	v_addc_co_u32_e32 v29, vcc, 0, v9, vcc
	v_add_co_u32_e32 v30, vcc, 0x12000, v8
	s_nop 1
	v_addc_co_u32_e32 v31, vcc, 0, v9, vcc
	v_add_co_u32_e32 v32, vcc, 0x14000, v8
	s_nop 1
	v_addc_co_u32_e32 v33, vcc, 0, v9, vcc
	v_add_co_u32_e32 v34, vcc, 0x16000, v8
	s_nop 1
	v_addc_co_u32_e32 v35, vcc, 0, v9, vcc
	v_add_co_u32_e32 v36, vcc, 0x18000, v8
	s_nop 1
	v_addc_co_u32_e32 v37, vcc, 0, v9, vcc
	v_add_co_u32_e32 v38, vcc, 0x1a000, v8
	s_nop 1
	v_addc_co_u32_e32 v39, vcc, 0, v9, vcc
	v_add_co_u32_e32 v40, vcc, 0x1c000, v8
	s_nop 1
	v_addc_co_u32_e32 v41, vcc, 0, v9, vcc
	global_load_dword v49, v[26:27], off
	global_load_dword v50, v[28:29], off offset:3584
	global_load_dword v51, v[30:31], off offset:3072
	global_load_dword v52, v[32:33], off offset:2560
	global_load_dword v53, v[34:35], off offset:2048
	global_load_dword v54, v[36:37], off offset:1536
	global_load_dword v55, v[38:39], off offset:1024
	global_load_dword v56, v[40:41], off offset:512
	v_add_co_u32_e32 v26, vcc, 0x1e000, v8
	s_nop 1
	v_addc_co_u32_e32 v27, vcc, 0, v9, vcc
	v_add_co_u32_e32 v28, vcc, 0x1f000, v8
	s_nop 1
	v_addc_co_u32_e32 v29, vcc, 0, v9, vcc
	v_add_co_u32_e32 v30, vcc, 0x21000, v8
	s_nop 1
	v_addc_co_u32_e32 v31, vcc, 0, v9, vcc
	v_add_co_u32_e32 v32, vcc, 0x23000, v8
	s_nop 1
	v_addc_co_u32_e32 v33, vcc, 0, v9, vcc
	v_add_co_u32_e32 v34, vcc, 0x25000, v8
	s_nop 1
	v_addc_co_u32_e32 v35, vcc, 0, v9, vcc
	v_add_co_u32_e32 v36, vcc, 0x27000, v8
	s_nop 1
	v_addc_co_u32_e32 v37, vcc, 0, v9, vcc
	v_add_co_u32_e32 v38, vcc, 0x29000, v8
	s_nop 1
	v_addc_co_u32_e32 v39, vcc, 0, v9, vcc
	v_add_co_u32_e32 v40, vcc, 0x2b000, v8
	s_nop 1
	v_addc_co_u32_e32 v41, vcc, 0, v9, vcc
	global_load_dword v57, v[26:27], off
	global_load_dword v58, v[28:29], off offset:3584
	global_load_dword v59, v[30:31], off offset:3072
	global_load_dword v60, v[32:33], off offset:2560
	global_load_dword v61, v[34:35], off offset:2048
	global_load_dword v62, v[36:37], off offset:1536
	global_load_dword v63, v[38:39], off offset:1024
	global_load_dword v64, v[40:41], off offset:512
	v_add_co_u32_e32 v26, vcc, 0x2d000, v8
	s_nop 1
	v_addc_co_u32_e32 v27, vcc, 0, v9, vcc
	v_add_co_u32_e32 v28, vcc, 0x2e000, v8
	s_nop 1
	v_addc_co_u32_e32 v29, vcc, 0, v9, vcc
	v_add_co_u32_e32 v30, vcc, 0x30000, v8
	s_nop 1
	v_addc_co_u32_e32 v31, vcc, 0, v9, vcc
	v_add_co_u32_e32 v32, vcc, 0x32000, v8
	s_nop 1
	v_addc_co_u32_e32 v33, vcc, 0, v9, vcc
	v_add_co_u32_e32 v34, vcc, 0x34000, v8
	s_nop 1
	v_addc_co_u32_e32 v35, vcc, 0, v9, vcc
	v_add_co_u32_e32 v36, vcc, 0x36000, v8
	s_nop 1
	v_addc_co_u32_e32 v37, vcc, 0, v9, vcc
	v_add_co_u32_e32 v38, vcc, 0x38000, v8
	s_nop 1
	v_addc_co_u32_e32 v39, vcc, 0, v9, vcc
	v_add_co_u32_e32 v40, vcc, 0x3a000, v8
	s_nop 1
	v_addc_co_u32_e32 v41, vcc, 0, v9, vcc
	global_load_dword v26, v[26:27], off
	s_nop 0
	global_load_dword v27, v[28:29], off offset:3584
	s_nop 0
	global_load_dword v28, v[30:31], off offset:3072
	global_load_dword v29, v[32:33], off offset:2560
	s_nop 0
	global_load_dword v30, v[34:35], off offset:2048
	global_load_dword v31, v[36:37], off offset:1536
	global_load_dword v32, v[38:39], off offset:1024
	global_load_dword v33, v[40:41], off offset:512
	v_lshlrev_b32_e32 v34, 16, v12
	v_and_b32_e32 v12, 0xffff0000, v12
	v_add_f32_e32 v35, 0, v34
	v_add_f32_e32 v36, 0, v12
	v_lshlrev_b32_e32 v37, 16, v5
	v_and_b32_e32 v5, 0xffff0000, v5
	v_add_f32_e32 v35, v35, v37
	v_add_f32_e32 v36, v36, v5
	v_lshlrev_b32_e32 v38, 16, v15
	v_and_b32_e32 v15, 0xffff0000, v15
	v_add_f32_e32 v35, v35, v38
	v_add_f32_e32 v36, v36, v15
	v_lshlrev_b32_e32 v39, 16, v14
	v_and_b32_e32 v14, 0xffff0000, v14
	v_add_f32_e32 v35, v35, v39
	v_add_f32_e32 v36, v36, v14
	v_lshlrev_b32_e32 v40, 16, v19
	v_and_b32_e32 v41, 0xffff0000, v19
	v_add_f32_e32 v35, v35, v40
	v_add_f32_e32 v19, v36, v41
	v_lshlrev_b32_e32 v36, 16, v18
	v_add_f32_e32 v35, v35, v36
	v_add_f32_e32 v18, v19, v65
	v_add_f32_e32 v19, v35, v66
	v_add_f32_e32 v18, v18, v23
	s_waitcnt vmcnt(31)
	v_lshlrev_b32_e32 v35, 16, v25
	v_and_b32_e32 v25, 0xffff0000, v25
	v_add_f32_e32 v19, v19, v35
	v_add_f32_e32 v18, v18, v25
	v_fma_f32 v67, v24, v19, -v35
	v_fma_f32 v24, v24, v18, -v25
	v_cvt_pk_bf16_f32 v24, v67, v24
	global_store_dword v[6:7], v24, off sc1
	v_sub_f32_e32 v19, v19, v34
	v_sub_f32_e32 v12, v18, v12
	s_waitcnt vmcnt(31)
; __device__ __forceinline__ unsigned cvt_pk_bf16(float lo, float hi) { unsigned r; asm volatile("v_cvt_pk_bf16_f32 %0, %1, %2" : "=v"(r) : "v"(lo), "v"(hi)); return r; }
; __device__ __forceinline__ float bf_lo(unsigned w) { return __uint_as_float(w << 16); }
; __device__ __forceinline__ float bf_hi(unsigned w) { return __uint_as_float(w & 0xffff0000u); }
; template <int W> __device__ __forceinline__ void pool_item(const bf16* zp, bf16* pl, int t0) {
;     unsigned zr[W - 1 + 32];
; #pragma unroll
;     for (int j = 0; j < W - 1 + 32; ++j) { const int tt = j - (W - 1); zr[j] = (t0 + tt >= 0) ? *(const unsigned*)(zp + (long)tt * NIN) : 0u; }
;     float s0 = 0.f, s1 = 0.f;
; #pragma unroll
;     for (int j = 0; j < W - 1; ++j) { s0 += pg8::bf_lo(zr[j]); s1 += pg8::bf_hi(zr[j]); }
; #pragma unroll
;     for (int tt = 0; tt < 32; ++tt) { const float z0 = pg8::bf_lo(zr[W - 1 + tt]), z1 = pg8::bf_hi(zr[W - 1 + tt]); s0 += z0; s1 += z1; const int t = t0 + tt;
;         const float iv = (t + 1 >= W ? 1.0f / (float)W : 1.0f / (float)(t + 1));
;         *(unsigned*)(pl + (size_t)tt * PW) = pg8::cvt_pk_bf16(s0 * iv - z0, s1 * iv - z1);
;         s0 -= pg8::bf_lo(zr[tt]); s1 -= pg8::bf_hi(zr[tt]); }
	v_lshlrev_b32_e32 v24, 16, v42
	v_and_b32_e32 v34, 0xffff0000, v42
	v_add_f32_e32 v18, v19, v24
	v_add_f32_e32 v12, v12, v34
	v_fma_f32 v19, v22, v18, -v24
	v_fma_f32 v22, v22, v12, -v34
	v_cvt_pk_bf16_f32 v19, v19, v22
	v_sub_f32_e32 v18, v18, v37
	v_sub_f32_e32 v5, v12, v5
	s_waitcnt vmcnt(30)
	v_lshlrev_b32_e32 v12, 16, v43
	v_and_b32_e32 v22, 0xffff0000, v43
	v_add_f32_e32 v18, v18, v12
	v_add_f32_e32 v5, v5, v22
	global_store_dword v[6:7], v19, off offset:1024 sc1
	v_fma_f32 v19, v21, v18, -v12
	v_fma_f32 v21, v21, v5, -v22
	v_cvt_pk_bf16_f32 v19, v19, v21
	v_sub_f32_e32 v18, v18, v38
	v_sub_f32_e32 v5, v5, v15
	s_waitcnt vmcnt(30)
	v_lshlrev_b32_e32 v21, 16, v44
	v_and_b32_e32 v37, 0xffff0000, v44
	v_add_f32_e32 v15, v18, v21
	v_add_f32_e32 v5, v5, v37
	global_store_dword v[6:7], v19, off offset:2048 sc1
	v_fma_f32 v18, v20, v15, -v21
	v_fma_f32 v19, v20, v5, -v37
	v_sub_f32_e32 v15, v15, v39
	s_waitcnt vmcnt(30)
	v_lshlrev_b32_e32 v20, 16, v45
	v_sub_f32_e32 v5, v5, v14
	v_and_b32_e32 v38, 0xffff0000, v45
	v_add_f32_e32 v39, v15, v20
	v_add_f32_e32 v5, v5, v38
	v_fma_f32 v14, v17, v39, -v20
	v_cvt_pk_bf16_f32 v18, v18, v19
	global_store_dword v[6:7], v18, off offset:3072 sc1
	v_fma_f32 v15, v17, v5, -v38
	v_cvt_pk_bf16_f32 v17, v14, v15
	v_add_co_u32_e32 v14, vcc, s14, v6
	v_sub_f32_e32 v5, v5, v41
	s_nop 0
	v_addc_co_u32_e32 v15, vcc, 0, v7, vcc
	v_add_co_u32_e32 v18, vcc, s62, v6
	v_sub_f32_e32 v39, v39, v40
	s_nop 0
	v_addc_co_u32_e32 v19, vcc, 0, v7, vcc
	global_store_dword v[18:19], v17, off offset:-4096 sc1
	s_waitcnt vmcnt(31)
	v_and_b32_e32 v17, 0xffff0000, v46
	v_lshlrev_b32_e32 v40, 16, v46
	v_add_f32_e32 v5, v5, v17
	v_add_f32_e32 v39, v39, v40
	v_fma_f32 v41, v16, v39, -v40
	v_fma_f32 v16, v16, v5, -v17
	v_cvt_pk_bf16_f32 v16, v41, v16
	global_store_dword v[14:15], v16, off offset:1024 sc1
	v_sub_f32_e32 v16, v39, v36
	v_sub_f32_e32 v5, v5, v65
	s_waitcnt vmcnt(31)
	v_lshlrev_b32_e32 v36, 16, v47
	v_and_b32_e32 v39, 0xffff0000, v47
	v_add_f32_e32 v16, v16, v36
	v_add_f32_e32 v5, v5, v39
	v_fma_f32 v41, v13, v16, -v36
	v_fma_f32 v13, v13, v5, -v39
	v_cvt_pk_bf16_f32 v13, v41, v13
	global_store_dword v[14:15], v13, off offset:2048 sc1
	s_waitcnt vmcnt(31)
	v_lshlrev_b32_e32 v41, 16, v48
	v_sub_f32_e32 v13, v16, v66
	v_and_b32_e32 v42, 0xffff0000, v48
	v_sub_f32_e32 v5, v5, v23
	v_add_f32_e32 v13, v13, v41
	v_add_f32_e32 v5, v5, v42
	v_fma_f32 v16, v13, s66, -v41
	v_fma_f32 v23, v5, s66, -v42
	v_cvt_pk_bf16_f32 v16, v16, v23
	global_store_dword v[14:15], v16, off offset:3072 sc1
	s_waitcnt vmcnt(31)
	v_lshlrev_b32_e32 v16, 16, v49
	v_sub_f32_e32 v13, v13, v35
	v_and_b32_e32 v23, 0xffff0000, v49
	v_sub_f32_e32 v5, v5, v25
	v_add_f32_e32 v13, v13, v16
	v_add_f32_e32 v5, v5, v23
	v_fma_f32 v14, v13, s66, -v16
	s_waitcnt vmcnt(30)
	v_lshlrev_b32_e32 v25, 16, v50
	v_sub_f32_e32 v13, v13, v24
	v_fma_f32 v15, v5, s66, -v23
	v_and_b32_e32 v35, 0xffff0000, v50
	v_sub_f32_e32 v5, v5, v34
	v_add_f32_e32 v13, v13, v25
	v_cvt_pk_bf16_f32 v14, v14, v15
	v_add_f32_e32 v5, v5, v35
	s_waitcnt vmcnt(29)
	v_lshlrev_b32_e32 v24, 16, v51
	v_sub_f32_e32 v12, v13, v12
	global_store_dword v[18:19], v14, off sc1
	v_fma_f32 v14, v13, s66, -v25
	v_fma_f32 v15, v5, s66, -v35
	v_and_b32_e32 v34, 0xffff0000, v51
	v_sub_f32_e32 v5, v5, v22
	v_add_f32_e32 v12, v12, v24
	v_cvt_pk_bf16_f32 v14, v14, v15
	v_add_f32_e32 v5, v5, v34
	v_fma_f32 v13, v12, s66, -v24
	s_waitcnt vmcnt(29)
	v_lshlrev_b32_e32 v22, 16, v52
	v_sub_f32_e32 v12, v12, v21
	global_store_dword v[18:19], v14, off offset:1024 sc1
	v_fma_f32 v14, v5, s66, -v34
	v_cvt_pk_bf16_f32 v13, v13, v14
	v_and_b32_e32 v43, 0xffff0000, v52
	v_sub_f32_e32 v5, v5, v37
	v_add_f32_e32 v12, v12, v22
	global_store_dword v[18:19], v13, off offset:2048 sc1
	v_add_f32_e32 v5, v5, v43
	v_fma_f32 v13, v12, s66, -v22
	v_fma_f32 v14, v5, s66, -v43
	v_cvt_pk_bf16_f32 v13, v13, v14
	global_store_dword v[18:19], v13, off offset:3072 sc1
	s_waitcnt vmcnt(31)
	v_lshlrev_b32_e32 v18, 16, v53
	v_sub_f32_e32 v12, v12, v20
	v_and_b32_e32 v19, 0xffff0000, v53
	v_sub_f32_e32 v5, v5, v38
	v_add_f32_e32 v20, v12, v18
	v_add_f32_e32 v5, v5, v19
	v_fma_f32 v12, v20, s66, -v18
	v_fma_f32 v13, v5, s66, -v19
	v_cvt_pk_bf16_f32 v21, v12, v13
	v_add_co_u32_e32 v12, vcc, s15, v6
	v_sub_f32_e32 v5, v5, v17
	s_nop 0
	v_addc_co_u32_e32 v13, vcc, 0, v7, vcc
	v_add_co_u32_e32 v14, vcc, s64, v6
	v_sub_f32_e32 v17, v20, v40
	s_nop 0
	v_addc_co_u32_e32 v15, vcc, 0, v7, vcc
	global_store_dword v[14:15], v21, off offset:-4096 sc1
	s_waitcnt vmcnt(31)
	v_lshlrev_b32_e32 v21, 16, v54
	v_and_b32_e32 v37, 0xffff0000, v54
	v_add_f32_e32 v17, v17, v21
	v_add_f32_e32 v5, v5, v37
	v_fma_f32 v20, v17, s66, -v21
	v_fma_f32 v38, v5, s66, -v37
	v_cvt_pk_bf16_f32 v20, v20, v38
	global_store_dword v[12:13], v20, off offset:1024 sc1
	s_waitcnt vmcnt(31)
	v_lshlrev_b32_e32 v20, 16, v55
	v_sub_f32_e32 v17, v17, v36
	v_and_b32_e32 v38, 0xffff0000, v55
	v_sub_f32_e32 v5, v5, v39
	v_add_f32_e32 v17, v17, v20
	v_add_f32_e32 v5, v5, v38
	v_fma_f32 v36, v17, s66, -v20
	v_fma_f32 v39, v5, s66, -v38
	v_cvt_pk_bf16_f32 v36, v36, v39
	global_store_dword v[12:13], v36, off offset:2048 sc1
	s_waitcnt vmcnt(31)
	v_lshlrev_b32_e32 v36, 16, v56
	v_sub_f32_e32 v17, v17, v41
	v_and_b32_e32 v39, 0xffff0000, v56
	v_sub_f32_e32 v5, v5, v42
	v_add_f32_e32 v17, v17, v36
	v_add_f32_e32 v5, v5, v39
	v_fma_f32 v40, v17, s66, -v36
	v_fma_f32 v41, v5, s66, -v39
	v_cvt_pk_bf16_f32 v40, v40, v41
	global_store_dword v[12:13], v40, off offset:3072 sc1
	s_waitcnt vmcnt(31)
; __device__ __forceinline__ unsigned cvt_pk_bf16(float lo, float hi) { unsigned r; asm volatile("v_cvt_pk_bf16_f32 %0, %1, %2" : "=v"(r) : "v"(lo), "v"(hi)); return r; }
; __device__ __forceinline__ float bf_lo(unsigned w) { return __uint_as_float(w << 16); }
; __device__ __forceinline__ float bf_hi(unsigned w) { return __uint_as_float(w & 0xffff0000u); }
; template <int W> __device__ __forceinline__ void pool_item(const bf16* zp, bf16* pl, int t0) {
;     unsigned zr[W - 1 + 32];
; #pragma unroll
;     for (int j = 0; j < W - 1 + 32; ++j) { const int tt = j - (W - 1); zr[j] = (t0 + tt >= 0) ? *(const unsigned*)(zp + (long)tt * NIN) : 0u; }
;     float s0 = 0.f, s1 = 0.f;
; #pragma unroll
;     for (int j = 0; j < W - 1; ++j) { s0 += pg8::bf_lo(zr[j]); s1 += pg8::bf_hi(zr[j]); }
; #pragma unroll
;     for (int tt = 0; tt < 32; ++tt) { const float z0 = pg8::bf_lo(zr[W - 1 + tt]), z1 = pg8::bf_hi(zr[W - 1 + tt]); s0 += z0; s1 += z1; const int t = t0 + tt;
;         const float iv = (t + 1 >= W ? 1.0f / (float)W : 1.0f / (float)(t + 1));
;         *(unsigned*)(pl + (size_t)tt * PW) = pg8::cvt_pk_bf16(s0 * iv - z0, s1 * iv - z1);
;         s0 -= pg8::bf_lo(zr[tt]); s1 -= pg8::bf_hi(zr[tt]); }
	v_lshlrev_b32_e32 v40, 16, v57
	v_and_b32_e32 v41, 0xffff0000, v57
	v_sub_f32_e32 v5, v5, v23
	v_sub_f32_e32 v12, v17, v16
	v_add_f32_e32 v5, v5, v41
	v_add_f32_e32 v12, v12, v40
	v_fma_f32 v13, v12, s66, -v40
	v_fma_f32 v16, v5, s66, -v41
	v_cvt_pk_bf16_f32 v13, v13, v16
	s_waitcnt vmcnt(30)
	v_lshlrev_b32_e32 v16, 16, v58
	v_and_b32_e32 v17, 0xffff0000, v58
	v_sub_f32_e32 v5, v5, v35
	v_sub_f32_e32 v12, v12, v25
	v_add_f32_e32 v5, v5, v17
	v_add_f32_e32 v12, v12, v16
	global_store_dword v[14:15], v13, off sc1
	v_fma_f32 v13, v12, s66, -v16
	v_fma_f32 v23, v5, s66, -v17
	v_cvt_pk_bf16_f32 v13, v13, v23
	s_waitcnt vmcnt(30)
	v_lshlrev_b32_e32 v23, 16, v59
	v_and_b32_e32 v25, 0xffff0000, v59
	v_sub_f32_e32 v5, v5, v34
	v_sub_f32_e32 v12, v12, v24
	v_add_f32_e32 v5, v5, v25
	v_add_f32_e32 v12, v12, v23
	global_store_dword v[14:15], v13, off offset:1024 sc1
	v_fma_f32 v13, v12, s66, -v23
	v_fma_f32 v24, v5, s66, -v25
	v_cvt_pk_bf16_f32 v13, v13, v24
	s_waitcnt vmcnt(30)
	v_lshlrev_b32_e32 v24, 16, v60
	v_and_b32_e32 v34, 0xffff0000, v60
	v_sub_f32_e32 v5, v5, v43
	v_sub_f32_e32 v12, v12, v22
	v_add_f32_e32 v5, v5, v34
	v_add_f32_e32 v12, v12, v24
	global_store_dword v[14:15], v13, off offset:2048 sc1
	v_fma_f32 v13, v12, s66, -v24
	v_fma_f32 v22, v5, s66, -v34
	v_cvt_pk_bf16_f32 v13, v13, v22
	s_waitcnt vmcnt(30)
	v_lshlrev_b32_e32 v22, 16, v61
	v_sub_f32_e32 v12, v12, v18
	v_and_b32_e32 v35, 0xffff0000, v61
	v_sub_f32_e32 v5, v5, v19
	v_add_f32_e32 v18, v12, v22
	v_add_f32_e32 v5, v5, v35
	v_fma_f32 v12, v18, s66, -v22
	global_store_dword v[14:15], v13, off offset:3072 sc1
	v_fma_f32 v13, v5, s66, -v35
	v_cvt_pk_bf16_f32 v19, v12, v13
	v_add_co_u32_e32 v12, vcc, s17, v6
	v_sub_f32_e32 v18, v18, v21
	s_nop 0
	v_addc_co_u32_e32 v13, vcc, 0, v7, vcc
	v_add_co_u32_e32 v14, vcc, s65, v6
	s_waitcnt vmcnt(30)
	v_and_b32_e32 v42, 0xffff0000, v62
	v_addc_co_u32_e32 v15, vcc, 0, v7, vcc
	global_store_dword v[14:15], v19, off offset:-4096 sc1
	v_lshlrev_b32_e32 v19, 16, v62
	v_sub_f32_e32 v5, v5, v37
	v_add_f32_e32 v18, v18, v19
	v_add_f32_e32 v5, v5, v42
	v_fma_f32 v21, v18, s66, -v19
	v_fma_f32 v37, v5, s66, -v42
	v_cvt_pk_bf16_f32 v21, v21, v37
	global_store_dword v[12:13], v21, off offset:1024 sc1
	s_waitcnt vmcnt(31)
	v_lshlrev_b32_e32 v21, 16, v63
	v_sub_f32_e32 v18, v18, v20
	v_and_b32_e32 v37, 0xffff0000, v63
	v_sub_f32_e32 v5, v5, v38
	v_add_f32_e32 v18, v18, v21
	v_add_f32_e32 v5, v5, v37
	v_fma_f32 v20, v18, s66, -v21
	v_fma_f32 v38, v5, s66, -v37
	v_cvt_pk_bf16_f32 v20, v20, v38
	global_store_dword v[12:13], v20, off offset:2048 sc1
	s_waitcnt vmcnt(31)
	v_lshlrev_b32_e32 v20, 16, v64
	v_sub_f32_e32 v18, v18, v36
	v_and_b32_e32 v38, 0xffff0000, v64
	v_sub_f32_e32 v5, v5, v39
	v_add_f32_e32 v18, v18, v20
	v_add_f32_e32 v5, v5, v38
	v_fma_f32 v36, v18, s66, -v20
	v_fma_f32 v39, v5, s66, -v38
	v_cvt_pk_bf16_f32 v36, v36, v39
	global_store_dword v[12:13], v36, off offset:3072 sc1
	v_sub_f32_e32 v5, v5, v41
	s_waitcnt vmcnt(31)
	v_and_b32_e32 v12, 0xffff0000, v26
	v_add_f32_e32 v5, v5, v12
	v_sub_f32_e32 v13, v18, v40
	v_lshlrev_b32_e32 v18, 16, v26
	v_add_f32_e32 v13, v13, v18
	v_fma_f32 v12, v5, s66, -v12
	v_fma_f32 v18, v13, s66, -v18
	v_cvt_pk_bf16_f32 v12, v18, v12
	global_store_dword v[14:15], v12, off sc1
	v_sub_f32_e32 v5, v5, v17
	s_waitcnt vmcnt(31)
	v_and_b32_e32 v12, 0xffff0000, v27
	v_add_f32_e32 v5, v5, v12
	v_sub_f32_e32 v13, v13, v16
	v_lshlrev_b32_e32 v16, 16, v27
	v_add_f32_e32 v13, v13, v16
	v_fma_f32 v12, v5, s66, -v12
	v_fma_f32 v16, v13, s66, -v16
	v_cvt_pk_bf16_f32 v12, v16, v12
	global_store_dword v[14:15], v12, off offset:1024 sc1
	v_sub_f32_e32 v5, v5, v25
	s_waitcnt vmcnt(31)
	v_and_b32_e32 v12, 0xffff0000, v28
	v_add_f32_e32 v5, v5, v12
	v_sub_f32_e32 v13, v13, v23
	v_lshlrev_b32_e32 v16, 16, v28
	v_add_f32_e32 v13, v13, v16
	v_fma_f32 v12, v5, s66, -v12
	v_fma_f32 v16, v13, s66, -v16
	v_cvt_pk_bf16_f32 v12, v16, v12
	global_store_dword v[14:15], v12, off offset:2048 sc1
	v_sub_f32_e32 v5, v5, v34
	s_waitcnt vmcnt(31)
	v_and_b32_e32 v12, 0xffff0000, v29
	v_add_f32_e32 v5, v5, v12
	v_sub_f32_e32 v13, v13, v24
	v_lshlrev_b32_e32 v16, 16, v29
	v_add_f32_e32 v13, v13, v16
	v_fma_f32 v12, v5, s66, -v12
	v_fma_f32 v16, v13, s66, -v16
	v_cvt_pk_bf16_f32 v12, v16, v12
	global_store_dword v[14:15], v12, off offset:3072 sc1
	v_sub_f32_e32 v5, v5, v35
	s_waitcnt vmcnt(31)
	v_and_b32_e32 v12, 0xffff0000, v30
	v_add_f32_e32 v5, v5, v12
	v_sub_f32_e32 v13, v13, v22
	v_lshlrev_b32_e32 v14, 16, v30
	v_add_f32_e32 v15, v13, v14
	v_fma_f32 v12, v5, s66, -v12
	v_fma_f32 v13, v15, s66, -v14
	v_cvt_pk_bf16_f32 v14, v13, v12
	v_add_co_u32_e32 v12, vcc, s18, v6
	v_sub_f32_e32 v5, v5, v42
	s_nop 0
	v_addc_co_u32_e32 v13, vcc, 0, v7, vcc
	global_store_dword v[12:13], v14, off sc1
	s_waitcnt vmcnt(31)
	v_and_b32_e32 v14, 0xffff0000, v31
	v_add_f32_e32 v5, v5, v14
	v_sub_f32_e32 v15, v15, v19
	v_lshlrev_b32_e32 v16, 16, v31
	v_add_f32_e32 v15, v15, v16
	v_fma_f32 v14, v5, s66, -v14
	v_fma_f32 v16, v15, s66, -v16
	v_cvt_pk_bf16_f32 v14, v16, v14
	global_store_dword v[12:13], v14, off offset:1024 sc1
	v_sub_f32_e32 v5, v5, v37
	s_waitcnt vmcnt(31)
	v_and_b32_e32 v14, 0xffff0000, v32
	v_add_f32_e32 v5, v5, v14
	v_sub_f32_e32 v15, v15, v21
	v_lshlrev_b32_e32 v16, 16, v32
	v_add_f32_e32 v15, v15, v16
	v_fma_f32 v14, v5, s66, -v14
	v_fma_f32 v16, v15, s66, -v16
	v_cvt_pk_bf16_f32 v14, v16, v14
	global_store_dword v[12:13], v14, off offset:2048 sc1
	v_sub_f32_e32 v5, v5, v38
	s_waitcnt vmcnt(31)
	v_and_b32_e32 v12, 0xffff0000, v33
	v_add_f32_e32 v5, v5, v12
	v_sub_f32_e32 v13, v15, v20
	v_lshlrev_b32_e32 v14, 16, v33
	v_add_f32_e32 v13, v13, v14
	v_fma_f32 v5, v5, s66, -v12
	v_fma_f32 v13, v13, s66, -v14
	v_cvt_pk_bf16_f32 v5, v13, v5

; __device__ __forceinline__ unsigned cvt_pk_bf16(float lo, float hi) { unsigned r; asm volatile("v_cvt_pk_bf16_f32 %0, %1, %2" : "=v"(r) : "v"(lo), "v"(hi)); return r; }
; __device__ __forceinline__ float bf_lo(unsigned w) { return __uint_as_float(w << 16); }
; __device__ __forceinline__ float bf_hi(unsigned w) { return __uint_as_float(w & 0xffff0000u); }
; template <int W> __device__ __forceinline__ void pool_item(const bf16* zp, bf16* pl, int t0) {
;     unsigned zr[W - 1 + 32];
; #pragma unroll
;     for (int j = 0; j < W - 1 + 32; ++j) { const int tt = j - (W - 1); zr[j] = (t0 + tt >= 0) ? *(const unsigned*)(zp + (long)tt * NIN) : 0u; }
;     float s0 = 0.f, s1 = 0.f;
; #pragma unroll
;     for (int j = 0; j < W - 1; ++j) { s0 += pg8::bf_lo(zr[j]); s1 += pg8::bf_hi(zr[j]); }
; #pragma unroll
;     for (int tt = 0; tt < 32; ++tt) { const float z0 = pg8::bf_lo(zr[W - 1 + tt]), z1 = pg8::bf_hi(zr[W - 1 + tt]); s0 += z0; s1 += z1; const int t = t0 + tt;
;         const float iv = (t + 1 >= W ? 1.0f / (float)W : 1.0f / (float)(t + 1));
;         *(unsigned*)(pl + (size_t)tt * PW) = pg8::cvt_pk_bf16(s0 * iv - z0, s1 * iv - z1);
;         s0 -= pg8::bf_lo(zr[tt]); s1 -= pg8::bf_hi(zr[tt]); }
.LBB0_567:
	s_or_b64 exec, exec, s[6:7]
	v_add_co_u32_e32 v18, vcc, 0x1000, v8
	s_nop 1
	v_addc_co_u32_e32 v19, vcc, 0, v9, vcc
	v_add_co_u32_e32 v20, vcc, 0x3000, v8
	s_nop 1
	v_addc_co_u32_e32 v21, vcc, 0, v9, vcc
	v_add_co_u32_e32 v22, vcc, 0x5000, v8
	s_nop 1
	v_addc_co_u32_e32 v23, vcc, 0, v9, vcc
	v_add_co_u32_e32 v24, vcc, 0x7000, v8
	s_nop 1
	v_addc_co_u32_e32 v25, vcc, 0, v9, vcc
	v_add_co_u32_e32 v26, vcc, 0x9000, v8
	s_nop 1
	v_addc_co_u32_e32 v27, vcc, 0, v9, vcc
	v_add_co_u32_e32 v28, vcc, 0xb000, v8
	s_nop 1
	v_addc_co_u32_e32 v29, vcc, 0, v9, vcc
	v_add_co_u32_e32 v30, vcc, 0xd000, v8
	s_nop 1
	v_addc_co_u32_e32 v31, vcc, 0, v9, vcc
	global_load_dword v17, v[8:9], off
	global_load_dword v34, v[18:19], off offset:3584
	global_load_dword v35, v[20:21], off offset:3072
	global_load_dword v36, v[22:23], off offset:2560
	global_load_dword v37, v[24:25], off offset:2048
	global_load_dword v38, v[26:27], off offset:1536
	global_load_dword v39, v[28:29], off offset:1024
	global_load_dword v40, v[30:31], off offset:512
	v_add_co_u32_e32 v18, vcc, 0xf000, v8
	s_nop 1
	v_addc_co_u32_e32 v19, vcc, 0, v9, vcc
	v_add_co_u32_e32 v20, vcc, 0x10000, v8
	s_nop 1
	v_addc_co_u32_e32 v21, vcc, 0, v9, vcc
	v_add_co_u32_e32 v22, vcc, 0x12000, v8
	s_nop 1
	v_addc_co_u32_e32 v23, vcc, 0, v9, vcc
	v_add_co_u32_e32 v24, vcc, 0x14000, v8
	s_nop 1
	v_addc_co_u32_e32 v25, vcc, 0, v9, vcc
	v_add_co_u32_e32 v26, vcc, 0x16000, v8
	s_nop 1
	v_addc_co_u32_e32 v27, vcc, 0, v9, vcc
	v_add_co_u32_e32 v28, vcc, 0x18000, v8
	s_nop 1
	v_addc_co_u32_e32 v29, vcc, 0, v9, vcc
	v_add_co_u32_e32 v30, vcc, 0x1a000, v8
	s_nop 1
	v_addc_co_u32_e32 v31, vcc, 0, v9, vcc
	v_add_co_u32_e32 v32, vcc, 0x1c000, v8
	s_nop 1
	v_addc_co_u32_e32 v33, vcc, 0, v9, vcc
	global_load_dword v41, v[18:19], off
	global_load_dword v42, v[20:21], off offset:3584
	global_load_dword v43, v[22:23], off offset:3072
	global_load_dword v44, v[24:25], off offset:2560
	global_load_dword v45, v[26:27], off offset:2048
	global_load_dword v46, v[28:29], off offset:1536
	global_load_dword v47, v[30:31], off offset:1024
	global_load_dword v48, v[32:33], off offset:512
	v_add_co_u32_e32 v18, vcc, 0x1e000, v8
	s_nop 1
	v_addc_co_u32_e32 v19, vcc, 0, v9, vcc
	v_add_co_u32_e32 v20, vcc, 0x1f000, v8
	s_nop 1
	v_addc_co_u32_e32 v21, vcc, 0, v9, vcc
	v_add_co_u32_e32 v22, vcc, 0x21000, v8
	s_nop 1
	v_addc_co_u32_e32 v23, vcc, 0, v9, vcc
	v_add_co_u32_e32 v24, vcc, 0x23000, v8
	s_nop 1
	v_addc_co_u32_e32 v25, vcc, 0, v9, vcc
	v_add_co_u32_e32 v26, vcc, 0x25000, v8
	s_nop 1
	v_addc_co_u32_e32 v27, vcc, 0, v9, vcc
	v_add_co_u32_e32 v28, vcc, 0x27000, v8
	s_nop 1
	v_addc_co_u32_e32 v29, vcc, 0, v9, vcc
	v_add_co_u32_e32 v30, vcc, 0x29000, v8
	s_nop 1
	v_addc_co_u32_e32 v31, vcc, 0, v9, vcc
	v_add_co_u32_e32 v32, vcc, 0x2b000, v8
	s_nop 1
	v_addc_co_u32_e32 v33, vcc, 0, v9, vcc
	global_load_dword v49, v[18:19], off
	global_load_dword v50, v[20:21], off offset:3584
	global_load_dword v51, v[22:23], off offset:3072
	global_load_dword v52, v[24:25], off offset:2560
	global_load_dword v53, v[26:27], off offset:2048
	global_load_dword v54, v[28:29], off offset:1536
	global_load_dword v55, v[30:31], off offset:1024
	global_load_dword v56, v[32:33], off offset:512
	v_add_co_u32_e32 v18, vcc, 0x2d000, v8
	s_nop 1
	v_addc_co_u32_e32 v19, vcc, 0, v9, vcc
	v_add_co_u32_e32 v20, vcc, 0x2e000, v8
	s_nop 1
	v_addc_co_u32_e32 v21, vcc, 0, v9, vcc
	v_add_co_u32_e32 v22, vcc, 0x30000, v8
	s_nop 1
	v_addc_co_u32_e32 v23, vcc, 0, v9, vcc
	v_add_co_u32_e32 v24, vcc, 0x32000, v8
	s_nop 1
	v_addc_co_u32_e32 v25, vcc, 0, v9, vcc
	v_add_co_u32_e32 v26, vcc, 0x34000, v8
	s_nop 1
	v_addc_co_u32_e32 v27, vcc, 0, v9, vcc
	v_add_co_u32_e32 v28, vcc, 0x36000, v8
	s_nop 1
	v_addc_co_u32_e32 v29, vcc, 0, v9, vcc
	v_add_co_u32_e32 v30, vcc, 0x38000, v8
	s_nop 1
	v_addc_co_u32_e32 v31, vcc, 0, v9, vcc
	v_add_co_u32_e32 v32, vcc, 0x3a000, v8
	s_nop 1
	v_addc_co_u32_e32 v33, vcc, 0, v9, vcc
	global_load_dword v18, v[18:19], off
	s_nop 0
	global_load_dword v19, v[20:21], off offset:3584
	s_nop 0
	global_load_dword v20, v[22:23], off offset:3072
	global_load_dword v21, v[24:25], off offset:2560
	s_nop 0
	global_load_dword v22, v[26:27], off offset:2048
	global_load_dword v23, v[28:29], off offset:1536
	global_load_dword v24, v[30:31], off offset:1024
	global_load_dword v25, v[32:33], off offset:512
	s_waitcnt vmcnt(32)
	v_lshlrev_b32_e32 v26, 16, v12
	v_and_b32_e32 v12, 0xffff0000, v12
	v_add_f32_e32 v27, 0, v26
	v_add_f32_e32 v28, 0, v12
	v_lshlrev_b32_e32 v29, 16, v5
	v_and_b32_e32 v5, 0xffff0000, v5
	v_add_f32_e32 v27, v27, v29
	v_add_f32_e32 v28, v28, v5
	v_lshlrev_b32_e32 v30, 16, v16
	v_and_b32_e32 v16, 0xffff0000, v16
	v_add_f32_e32 v27, v27, v30
	v_add_f32_e32 v28, v28, v16
	s_waitcnt vmcnt(31)
	v_lshlrev_b32_e32 v31, 16, v17
	v_and_b32_e32 v17, 0xffff0000, v17
	v_add_f32_e32 v27, v27, v31
	v_add_f32_e32 v28, v28, v17
	v_fma_f32 v32, v15, v27, -v31
	v_fma_f32 v15, v15, v28, -v17
	v_cvt_pk_bf16_f32 v15, v32, v15
	global_store_dword v[6:7], v15, off sc1
	v_sub_f32_e32 v12, v28, v12
	s_waitcnt vmcnt(31)
	v_and_b32_e32 v28, 0xffff0000, v34
	v_sub_f32_e32 v15, v27, v26
	v_lshlrev_b32_e32 v26, 16, v34
	v_add_f32_e32 v12, v12, v28
	v_add_f32_e32 v15, v15, v26
	v_fma_f32 v27, v14, v15, -v26
	v_fma_f32 v14, v14, v12, -v28
	v_cvt_pk_bf16_f32 v14, v27, v14
	global_store_dword v[6:7], v14, off offset:1024 sc1
	v_sub_f32_e32 v14, v15, v29
	v_sub_f32_e32 v5, v12, v5
	s_waitcnt vmcnt(31)
	v_lshlrev_b32_e32 v27, 16, v35
	v_and_b32_e32 v29, 0xffff0000, v35
	v_add_f32_e32 v12, v14, v27
	v_add_f32_e32 v5, v5, v29
	v_fma_f32 v14, v13, v12, -v27
	v_fma_f32 v13, v13, v5, -v29
	s_waitcnt vmcnt(30)
; __device__ __forceinline__ unsigned cvt_pk_bf16(float lo, float hi) { unsigned r; asm volatile("v_cvt_pk_bf16_f32 %0, %1, %2" : "=v"(r) : "v"(lo), "v"(hi)); return r; }
; __device__ __forceinline__ float bf_lo(unsigned w) { return __uint_as_float(w << 16); }
; __device__ __forceinline__ float bf_hi(unsigned w) { return __uint_as_float(w & 0xffff0000u); }
; template <int W> __device__ __forceinline__ void pool_item(const bf16* zp, bf16* pl, int t0) {
;     unsigned zr[W - 1 + 32];
; #pragma unroll
;     for (int j = 0; j < W - 1 + 32; ++j) { const int tt = j - (W - 1); zr[j] = (t0 + tt >= 0) ? *(const unsigned*)(zp + (long)tt * NIN) : 0u; }
;     float s0 = 0.f, s1 = 0.f;
; #pragma unroll
;     for (int j = 0; j < W - 1; ++j) { s0 += pg8::bf_lo(zr[j]); s1 += pg8::bf_hi(zr[j]); }
; #pragma unroll
;     for (int tt = 0; tt < 32; ++tt) { const float z0 = pg8::bf_lo(zr[W - 1 + tt]), z1 = pg8::bf_hi(zr[W - 1 + tt]); s0 += z0; s1 += z1; const int t = t0 + tt;
;         const float iv = (t + 1 >= W ? 1.0f / (float)W : 1.0f / (float)(t + 1));
;         *(unsigned*)(pl + (size_t)tt * PW) = pg8::cvt_pk_bf16(s0 * iv - z0, s1 * iv - z1);
;         s0 -= pg8::bf_lo(zr[tt]); s1 -= pg8::bf_hi(zr[tt]); }
	v_lshlrev_b32_e32 v32, 16, v36
	v_sub_f32_e32 v12, v12, v30
	v_cvt_pk_bf16_f32 v13, v14, v13
	v_and_b32_e32 v33, 0xffff0000, v36
	v_sub_f32_e32 v5, v5, v16
	v_add_f32_e32 v12, v12, v32
	global_store_dword v[6:7], v13, off offset:2048 sc1
	v_add_f32_e32 v5, v5, v33
	v_fma_f32 v13, v12, s67, -v32
	s_waitcnt vmcnt(30)
	v_lshlrev_b32_e32 v16, 16, v37
	v_sub_f32_e32 v12, v12, v31
	v_fma_f32 v14, v5, s67, -v33
	v_and_b32_e32 v30, 0xffff0000, v37
	v_sub_f32_e32 v5, v5, v17
	v_add_f32_e32 v17, v12, v16
	v_cvt_pk_bf16_f32 v13, v13, v14
	v_add_f32_e32 v5, v5, v30
	v_fma_f32 v12, v17, s67, -v16
	global_store_dword v[6:7], v13, off offset:3072 sc1
	v_fma_f32 v13, v5, s67, -v30
	v_cvt_pk_bf16_f32 v31, v12, v13
	v_add_co_u32_e32 v12, vcc, s14, v6
	v_sub_f32_e32 v17, v17, v26
	s_nop 0
	v_addc_co_u32_e32 v13, vcc, 0, v7, vcc
	v_add_co_u32_e32 v14, vcc, s62, v6
	s_waitcnt vmcnt(30)
	v_and_b32_e32 v34, 0xffff0000, v38
	v_addc_co_u32_e32 v15, vcc, 0, v7, vcc
	global_store_dword v[14:15], v31, off offset:-4096 sc1
	v_lshlrev_b32_e32 v31, 16, v38
	v_sub_f32_e32 v5, v5, v28
	v_add_f32_e32 v17, v17, v31
	v_add_f32_e32 v5, v5, v34
	v_fma_f32 v26, v17, s67, -v31
	v_fma_f32 v28, v5, s67, -v34
	v_cvt_pk_bf16_f32 v26, v26, v28
	global_store_dword v[12:13], v26, off offset:1024 sc1
	s_waitcnt vmcnt(31)
	v_lshlrev_b32_e32 v26, 16, v39
	v_sub_f32_e32 v17, v17, v27
	v_and_b32_e32 v28, 0xffff0000, v39
	v_sub_f32_e32 v5, v5, v29
	v_add_f32_e32 v17, v17, v26
	v_add_f32_e32 v5, v5, v28
	v_fma_f32 v27, v17, s67, -v26
	v_fma_f32 v29, v5, s67, -v28
	v_cvt_pk_bf16_f32 v27, v27, v29
	global_store_dword v[12:13], v27, off offset:2048 sc1
	s_waitcnt vmcnt(31)
	v_lshlrev_b32_e32 v27, 16, v40
	v_sub_f32_e32 v17, v17, v32
	v_and_b32_e32 v29, 0xffff0000, v40
	v_sub_f32_e32 v5, v5, v33
	v_add_f32_e32 v17, v17, v27
	v_add_f32_e32 v5, v5, v29
	v_fma_f32 v32, v17, s67, -v27
	v_fma_f32 v33, v5, s67, -v29
	v_cvt_pk_bf16_f32 v32, v32, v33
	global_store_dword v[12:13], v32, off offset:3072 sc1
	s_waitcnt vmcnt(31)
	v_lshlrev_b32_e32 v12, 16, v41
	v_sub_f32_e32 v16, v17, v16
	v_and_b32_e32 v13, 0xffff0000, v41
	v_sub_f32_e32 v5, v5, v30
	v_add_f32_e32 v16, v16, v12
	v_add_f32_e32 v5, v5, v13
	v_fma_f32 v17, v16, s67, -v12
	v_fma_f32 v30, v5, s67, -v13
	v_cvt_pk_bf16_f32 v17, v17, v30
	global_store_dword v[14:15], v17, off sc1
	s_waitcnt vmcnt(31)
	v_lshlrev_b32_e32 v17, 16, v42
	v_sub_f32_e32 v16, v16, v31
	v_and_b32_e32 v30, 0xffff0000, v42
	v_sub_f32_e32 v5, v5, v34
	v_add_f32_e32 v16, v16, v17
	v_add_f32_e32 v5, v5, v30
	v_fma_f32 v31, v16, s67, -v17
	v_fma_f32 v32, v5, s67, -v30
	v_cvt_pk_bf16_f32 v31, v31, v32
	global_store_dword v[14:15], v31, off offset:1024 sc1
	s_waitcnt vmcnt(31)
	v_lshlrev_b32_e32 v31, 16, v43
	v_sub_f32_e32 v16, v16, v26
	v_and_b32_e32 v32, 0xffff0000, v43
	v_sub_f32_e32 v5, v5, v28
	v_add_f32_e32 v16, v16, v31
	v_add_f32_e32 v5, v5, v32
	v_fma_f32 v26, v16, s67, -v31
	v_fma_f32 v28, v5, s67, -v32
	v_cvt_pk_bf16_f32 v26, v26, v28
	global_store_dword v[14:15], v26, off offset:2048 sc1
	s_waitcnt vmcnt(31)
	v_lshlrev_b32_e32 v26, 16, v44
	v_sub_f32_e32 v16, v16, v27
	v_and_b32_e32 v28, 0xffff0000, v44
	v_sub_f32_e32 v5, v5, v29
	v_add_f32_e32 v16, v16, v26
	v_add_f32_e32 v5, v5, v28
	v_fma_f32 v27, v16, s67, -v26
	v_fma_f32 v29, v5, s67, -v28
	v_cvt_pk_bf16_f32 v27, v27, v29
	global_store_dword v[14:15], v27, off offset:3072 sc1
	s_waitcnt vmcnt(31)
	v_lshlrev_b32_e32 v27, 16, v45
	v_sub_f32_e32 v12, v16, v12
	v_and_b32_e32 v29, 0xffff0000, v45
	v_sub_f32_e32 v5, v5, v13
	v_add_f32_e32 v16, v12, v27
	v_add_f32_e32 v5, v5, v29
	v_fma_f32 v12, v16, s67, -v27
	v_fma_f32 v13, v5, s67, -v29
	v_cvt_pk_bf16_f32 v33, v12, v13
	v_add_co_u32_e32 v12, vcc, s15, v6
	v_sub_f32_e32 v16, v16, v17
	s_nop 0
	v_addc_co_u32_e32 v13, vcc, 0, v7, vcc
	v_add_co_u32_e32 v14, vcc, s64, v6
	s_waitcnt vmcnt(30)
	v_and_b32_e32 v34, 0xffff0000, v46
	v_addc_co_u32_e32 v15, vcc, 0, v7, vcc
	global_store_dword v[14:15], v33, off offset:-4096 sc1
	v_lshlrev_b32_e32 v33, 16, v46
	v_sub_f32_e32 v5, v5, v30
	v_add_f32_e32 v16, v16, v33
	v_add_f32_e32 v5, v5, v34
	v_fma_f32 v17, v16, s67, -v33
	v_fma_f32 v30, v5, s67, -v34
	v_cvt_pk_bf16_f32 v17, v17, v30
	global_store_dword v[12:13], v17, off offset:1024 sc1
	s_waitcnt vmcnt(31)
	v_lshlrev_b32_e32 v17, 16, v47
	v_sub_f32_e32 v16, v16, v31
	v_and_b32_e32 v30, 0xffff0000, v47
	v_sub_f32_e32 v5, v5, v32
	v_add_f32_e32 v16, v16, v17
	v_add_f32_e32 v5, v5, v30
	v_fma_f32 v31, v16, s67, -v17
	v_fma_f32 v32, v5, s67, -v30
	v_cvt_pk_bf16_f32 v31, v31, v32
	global_store_dword v[12:13], v31, off offset:2048 sc1
	s_waitcnt vmcnt(31)
	v_lshlrev_b32_e32 v31, 16, v48
	v_sub_f32_e32 v16, v16, v26
	v_and_b32_e32 v32, 0xffff0000, v48
	v_sub_f32_e32 v5, v5, v28
	v_add_f32_e32 v16, v16, v31
	v_add_f32_e32 v5, v5, v32
	v_fma_f32 v26, v16, s67, -v31
	v_fma_f32 v28, v5, s67, -v32
	v_cvt_pk_bf16_f32 v26, v26, v28
	global_store_dword v[12:13], v26, off offset:3072 sc1
	s_waitcnt vmcnt(31)
	v_lshlrev_b32_e32 v12, 16, v49
	v_sub_f32_e32 v16, v16, v27
	v_and_b32_e32 v13, 0xffff0000, v49
	v_sub_f32_e32 v5, v5, v29
	v_add_f32_e32 v16, v16, v12
	v_add_f32_e32 v5, v5, v13
	v_fma_f32 v26, v16, s67, -v12
	v_fma_f32 v27, v5, s67, -v13
	v_cvt_pk_bf16_f32 v26, v26, v27
	global_store_dword v[14:15], v26, off sc1
	s_waitcnt vmcnt(31)
; __device__ __forceinline__ unsigned cvt_pk_bf16(float lo, float hi) { unsigned r; asm volatile("v_cvt_pk_bf16_f32 %0, %1, %2" : "=v"(r) : "v"(lo), "v"(hi)); return r; }
; __device__ __forceinline__ float bf_lo(unsigned w) { return __uint_as_float(w << 16); }
; __device__ __forceinline__ float bf_hi(unsigned w) { return __uint_as_float(w & 0xffff0000u); }
; template <int W> __device__ __forceinline__ void pool_item(const bf16* zp, bf16* pl, int t0) {
;     unsigned zr[W - 1 + 32];
; #pragma unroll
;     for (int j = 0; j < W - 1 + 32; ++j) { const int tt = j - (W - 1); zr[j] = (t0 + tt >= 0) ? *(const unsigned*)(zp + (long)tt * NIN) : 0u; }
;     float s0 = 0.f, s1 = 0.f;
; #pragma unroll
;     for (int j = 0; j < W - 1; ++j) { s0 += pg8::bf_lo(zr[j]); s1 += pg8::bf_hi(zr[j]); }
; #pragma unroll
;     for (int tt = 0; tt < 32; ++tt) { const float z0 = pg8::bf_lo(zr[W - 1 + tt]), z1 = pg8::bf_hi(zr[W - 1 + tt]); s0 += z0; s1 += z1; const int t = t0 + tt;
;         const float iv = (t + 1 >= W ? 1.0f / (float)W : 1.0f / (float)(t + 1));
;         *(unsigned*)(pl + (size_t)tt * PW) = pg8::cvt_pk_bf16(s0 * iv - z0, s1 * iv - z1);
;         s0 -= pg8::bf_lo(zr[tt]); s1 -= pg8::bf_hi(zr[tt]); }
	v_lshlrev_b32_e32 v26, 16, v50
	v_sub_f32_e32 v16, v16, v33
	v_and_b32_e32 v27, 0xffff0000, v50
	v_sub_f32_e32 v5, v5, v34
	v_add_f32_e32 v16, v16, v26
	v_add_f32_e32 v5, v5, v27
	v_fma_f32 v28, v16, s67, -v26
	v_fma_f32 v29, v5, s67, -v27
	v_cvt_pk_bf16_f32 v28, v28, v29
	global_store_dword v[14:15], v28, off offset:1024 sc1
	s_waitcnt vmcnt(31)
	v_lshlrev_b32_e32 v28, 16, v51
	v_sub_f32_e32 v16, v16, v17
	v_and_b32_e32 v29, 0xffff0000, v51
	v_sub_f32_e32 v5, v5, v30
	v_add_f32_e32 v16, v16, v28
	v_add_f32_e32 v5, v5, v29
	v_fma_f32 v17, v16, s67, -v28
	v_fma_f32 v30, v5, s67, -v29
	v_cvt_pk_bf16_f32 v17, v17, v30
	global_store_dword v[14:15], v17, off offset:2048 sc1
	s_waitcnt vmcnt(31)
	v_lshlrev_b32_e32 v17, 16, v52
	v_sub_f32_e32 v16, v16, v31
	v_and_b32_e32 v30, 0xffff0000, v52
	v_sub_f32_e32 v5, v5, v32
	v_add_f32_e32 v16, v16, v17
	v_add_f32_e32 v5, v5, v30
	v_fma_f32 v31, v16, s67, -v17
	v_fma_f32 v32, v5, s67, -v30
	v_cvt_pk_bf16_f32 v31, v31, v32
	global_store_dword v[14:15], v31, off offset:3072 sc1
	s_waitcnt vmcnt(31)
	v_lshlrev_b32_e32 v31, 16, v53
	v_sub_f32_e32 v12, v16, v12
	v_and_b32_e32 v32, 0xffff0000, v53
	v_sub_f32_e32 v5, v5, v13
	v_add_f32_e32 v16, v12, v31
	v_add_f32_e32 v5, v5, v32
	v_fma_f32 v12, v16, s67, -v31
	v_fma_f32 v13, v5, s67, -v32
	v_cvt_pk_bf16_f32 v33, v12, v13
	v_add_co_u32_e32 v12, vcc, s17, v6
	v_sub_f32_e32 v16, v16, v26
	s_nop 0
	v_addc_co_u32_e32 v13, vcc, 0, v7, vcc
	v_add_co_u32_e32 v14, vcc, s65, v6
	s_waitcnt vmcnt(30)
	v_and_b32_e32 v34, 0xffff0000, v54
	v_addc_co_u32_e32 v15, vcc, 0, v7, vcc
	global_store_dword v[14:15], v33, off offset:-4096 sc1
	v_lshlrev_b32_e32 v33, 16, v54
	v_sub_f32_e32 v5, v5, v27
	v_add_f32_e32 v16, v16, v33
	v_add_f32_e32 v5, v5, v34
	v_fma_f32 v26, v16, s67, -v33
	v_fma_f32 v27, v5, s67, -v34
	v_cvt_pk_bf16_f32 v26, v26, v27
	global_store_dword v[12:13], v26, off offset:1024 sc1
	s_waitcnt vmcnt(31)
	v_lshlrev_b32_e32 v26, 16, v55
	v_sub_f32_e32 v16, v16, v28
	v_and_b32_e32 v27, 0xffff0000, v55
	v_sub_f32_e32 v5, v5, v29
	v_add_f32_e32 v16, v16, v26
	v_add_f32_e32 v5, v5, v27
	v_fma_f32 v28, v16, s67, -v26
	v_fma_f32 v29, v5, s67, -v27
	v_cvt_pk_bf16_f32 v28, v28, v29
	global_store_dword v[12:13], v28, off offset:2048 sc1
	s_waitcnt vmcnt(31)
	v_lshlrev_b32_e32 v28, 16, v56
	v_sub_f32_e32 v16, v16, v17
	v_and_b32_e32 v29, 0xffff0000, v56
	v_sub_f32_e32 v5, v5, v30
	v_add_f32_e32 v16, v16, v28
	v_add_f32_e32 v5, v5, v29
	v_fma_f32 v17, v16, s67, -v28
	v_fma_f32 v30, v5, s67, -v29
	v_cvt_pk_bf16_f32 v17, v17, v30
	global_store_dword v[12:13], v17, off offset:3072 sc1
	s_waitcnt vmcnt(31)
	v_lshlrev_b32_e32 v12, 16, v18
	v_sub_f32_e32 v16, v16, v31
	v_and_b32_e32 v13, 0xffff0000, v18
	v_sub_f32_e32 v5, v5, v32
	v_add_f32_e32 v16, v16, v12
	v_add_f32_e32 v5, v5, v13
	v_fma_f32 v17, v16, s67, -v12
	v_fma_f32 v18, v5, s67, -v13
	v_cvt_pk_bf16_f32 v17, v17, v18
	global_store_dword v[14:15], v17, off sc1
	s_waitcnt vmcnt(31)
	v_lshlrev_b32_e32 v17, 16, v19
	v_sub_f32_e32 v16, v16, v33
	v_and_b32_e32 v18, 0xffff0000, v19
	v_sub_f32_e32 v5, v5, v34
	v_add_f32_e32 v16, v16, v17
	v_add_f32_e32 v5, v5, v18
	v_fma_f32 v19, v16, s67, -v17
	v_fma_f32 v30, v5, s67, -v18
	v_cvt_pk_bf16_f32 v19, v19, v30
	global_store_dword v[14:15], v19, off offset:1024 sc1
	s_waitcnt vmcnt(31)
	v_lshlrev_b32_e32 v19, 16, v20
	v_sub_f32_e32 v16, v16, v26
	v_and_b32_e32 v20, 0xffff0000, v20
	v_sub_f32_e32 v5, v5, v27
	v_add_f32_e32 v16, v16, v19
	v_add_f32_e32 v5, v5, v20
	v_fma_f32 v26, v16, s67, -v19
	v_fma_f32 v27, v5, s67, -v20
	v_cvt_pk_bf16_f32 v26, v26, v27
	global_store_dword v[14:15], v26, off offset:2048 sc1
	s_waitcnt vmcnt(31)
	v_lshlrev_b32_e32 v26, 16, v21
	v_sub_f32_e32 v16, v16, v28
	v_and_b32_e32 v21, 0xffff0000, v21
	v_sub_f32_e32 v5, v5, v29
	v_add_f32_e32 v16, v16, v26
	v_add_f32_e32 v5, v5, v21
	v_fma_f32 v27, v16, s67, -v26
	v_fma_f32 v28, v5, s67, -v21
	v_cvt_pk_bf16_f32 v27, v27, v28
	global_store_dword v[14:15], v27, off offset:3072 sc1
	v_sub_f32_e32 v12, v16, v12
	s_waitcnt vmcnt(31)
	v_lshlrev_b32_e32 v14, 16, v22
	v_sub_f32_e32 v5, v5, v13
	v_and_b32_e32 v13, 0xffff0000, v22
	v_add_f32_e32 v15, v12, v14
	v_add_f32_e32 v5, v5, v13
	v_fma_f32 v12, v15, s67, -v14
	v_fma_f32 v13, v5, s67, -v13
	v_cvt_pk_bf16_f32 v14, v12, v13
	v_add_co_u32_e32 v12, vcc, s18, v6
	v_sub_f32_e32 v5, v5, v18
	s_nop 0
	v_addc_co_u32_e32 v13, vcc, 0, v7, vcc
	global_store_dword v[12:13], v14, off sc1
	s_waitcnt vmcnt(31)
	v_and_b32_e32 v14, 0xffff0000, v23
	v_add_f32_e32 v5, v5, v14
	v_sub_f32_e32 v15, v15, v17
	v_lshlrev_b32_e32 v16, 16, v23
	v_add_f32_e32 v15, v15, v16
	v_fma_f32 v14, v5, s67, -v14
	v_fma_f32 v16, v15, s67, -v16
	v_cvt_pk_bf16_f32 v14, v16, v14
	global_store_dword v[12:13], v14, off offset:1024 sc1
	v_sub_f32_e32 v5, v5, v20
	s_waitcnt vmcnt(31)
	v_and_b32_e32 v14, 0xffff0000, v24
	v_add_f32_e32 v5, v5, v14
	v_sub_f32_e32 v15, v15, v19
	v_lshlrev_b32_e32 v16, 16, v24
	v_add_f32_e32 v15, v15, v16
	v_fma_f32 v14, v5, s67, -v14
	v_fma_f32 v16, v15, s67, -v16
	v_cvt_pk_bf16_f32 v14, v16, v14
	global_store_dword v[12:13], v14, off offset:2048 sc1
	v_sub_f32_e32 v5, v5, v21
	s_waitcnt vmcnt(31)
	v_and_b32_e32 v12, 0xffff0000, v25
	v_add_f32_e32 v5, v5, v12
	v_sub_f32_e32 v13, v15, v26
	v_lshlrev_b32_e32 v14, 16, v25
	v_add_f32_e32 v13, v13, v14
	v_fma_f32 v5, v5, s67, -v12
	v_fma_f32 v13, v13, s67, -v14
	v_cvt_pk_bf16_f32 v5, v13, v5
